# RWKV scan: staging waves fold lane-uniform pair corrections into the staged vectors + per-row record; scan pair = 18 pk + 8 dpp, 10 LDS reads
# speedup vs baseline: 1.0158x; 1.0158x over previous
.LBB0_649:
	s_and_b64 vcc, exec, s[0:1]
	s_cbranch_vccz .LBB0_676
	s_cmpk_lt_u32 s3, 0x100
	s_mov_b64 s[0:1], -1
	s_cbranch_scc0 .LBB0_654
	v_lshrrev_b32_e32 v1, 4, v152
	v_lshl_or_b32 v1, s50, 2, v1
	v_and_b32_e32 v118, 15, v153
	v_lshlrev_b32_e32 v6, 4, v118
	v_lshlrev_b32_e32 v7, 4, v1
	v_add_u32_e32 v7, 0x23600, v7
	v_lshlrev_b32_e32 v9, 6, v1
	v_lshl_add_u32 v9, v118, 2, v9
	v_add_u32_e32 v9, 0x9b00, v9
	v_mov_b32_e32 v2, 0
	v_mov_b32_e32 v3, 0
	v_mov_b32_e32 v4, 0
	v_mov_b32_e32 v5, 0
	s_mov_b32 s0, 0
	s_mov_b32 s1, 0x11b00
	s_mov_b32 vcc_lo, 0x1000
	s_waitcnt vmcnt(0) lgkmcnt(0)
	s_barrier
.LBB0_652:
	ds_read_b128 v[20:23], v6 offset:0
	ds_read_b128 v[24:27], v6 offset:256
	ds_read_b128 v[56:59], v7 offset:0
	ds_read_b128 v[28:31], v6 offset:512
	ds_read_b128 v[32:35], v6 offset:768
	ds_read_b128 v[36:39], v6 offset:1024
	ds_read_b128 v[40:43], v6 offset:1280
	ds_read_b128 v[48:51], v6 offset:1792
	ds_read_b128 v[44:47], v6 offset:1536
	ds_read_b128 v[52:55], v6 offset:2048
	s_waitcnt lgkmcnt(9)
	v_pk_mul_f32 v[10:11], v[2:3], v[20:21] op_sel_hi:[0,1]
	ds_read_b128 v[68:71], v6 offset:2304
	s_waitcnt lgkmcnt(8)
	v_pk_fma_f32 v[14:15], v[2:3], v[24:25], v[58:59] op_sel_hi:[0,1,1]
	v_pk_fma_f32 v[10:11], v[2:3], v[22:23], v[10:11] op_sel:[1,0,0] op_sel_hi:[1,1,1]
	ds_read_b128 v[72:75], v6 offset:2560
	v_pk_fma_f32 v[14:15], v[2:3], v[26:27], v[14:15] op_sel:[1,0,0] op_sel_hi:[1,1,1]
	s_waitcnt lgkmcnt(8)
	v_pk_fma_f32 v[10:11], v[4:5], v[28:29], v[10:11] op_sel_hi:[0,1,1]
	s_waitcnt lgkmcnt(7)
	v_pk_fma_f32 v[14:15], v[4:5], v[32:33], v[14:15] op_sel_hi:[0,1,1]
	ds_read_b128 v[104:107], v7 offset:256
	v_pk_fma_f32 v[10:11], v[4:5], v[30:31], v[10:11] op_sel:[1,0,0] op_sel_hi:[1,1,1]
	s_waitcnt lgkmcnt(7)
	v_pk_mul_f32 v[114:115], v[2:3], v[36:37]
	ds_read_b128 v[76:79], v6 offset:2816
	v_pk_mul_f32 v[116:117], v[4:5], v[38:39]
	v_add_f32_dpp v10, v10, v10 row_ror:8 row_mask:0xf bank_mask:0xf bound_ctrl:1
	v_add_f32_dpp v11, v11, v11 row_ror:8 row_mask:0xf bank_mask:0xf bound_ctrl:1
	ds_read_b128 v[80:83], v6 offset:3072
	v_pk_fma_f32 v[14:15], v[4:5], v[34:35], v[14:15] op_sel:[1,0,0] op_sel_hi:[1,1,1]
	v_add_f32_dpp v10, v10, v10 row_ror:4 row_mask:0xf bank_mask:0xf bound_ctrl:1
	ds_read_b128 v[84:87], v6 offset:3328
	v_add_f32_dpp v11, v11, v11 row_ror:4 row_mask:0xf bank_mask:0xf bound_ctrl:1
	s_waitcnt lgkmcnt(9)
	v_pk_fma_f32 v[114:115], v[40:41], v[56:57], v[114:115] op_sel_hi:[1,0,1]
	v_add_f32_dpp v10, v10, v10 row_ror:2 row_mask:0xf bank_mask:0xf bound_ctrl:1
	ds_read_b128 v[88:91], v6 offset:3584
	v_add_f32_dpp v11, v11, v11 row_ror:2 row_mask:0xf bank_mask:0xf bound_ctrl:1
	v_pk_fma_f32 v[116:117], v[42:43], v[56:57], v[116:117] op_sel_hi:[1,0,1]
	ds_read_b128 v[96:99], v6 offset:4096
	v_add_f32_dpp v10, v10, v10 row_ror:1 row_mask:0xf bank_mask:0xf bound_ctrl:1
	v_add_f32_dpp v11, v11, v11 row_ror:1 row_mask:0xf bank_mask:0xf bound_ctrl:1
	s_waitcnt lgkmcnt(10)
	v_pk_fma_f32 v[114:115], v[48:49], v[56:57], v[114:115] op_sel:[0,1,0] op_sel_hi:[1,1,1]
	ds_read_b128 v[92:95], v6 offset:3840
	v_pk_fma_f32 v[116:117], v[50:51], v[56:57], v[116:117] op_sel:[0,1,0] op_sel_hi:[1,1,1]
	s_waitcnt lgkmcnt(10)
	v_pk_fma_f32 v[114:115], v[44:45], v[10:11], v[114:115] op_sel_hi:[1,0,1] neg_lo:[1,0,0] neg_hi:[1,0,0]
	ds_read_b128 v[100:103], v6 offset:4352
	v_pk_fma_f32 v[116:117], v[46:47], v[10:11], v[116:117] op_sel_hi:[1,0,1] neg_lo:[1,0,0] neg_hi:[1,0,0]
	s_waitcnt lgkmcnt(10)
	v_pk_fma_f32 v[2:3], v[52:53], v[10:11], v[114:115] op_sel:[0,1,0] op_sel_hi:[1,1,1] neg_lo:[1,0,0] neg_hi:[1,0,0]
	v_pk_fma_f32 v[4:5], v[54:55], v[10:11], v[116:117] op_sel:[0,1,0] op_sel_hi:[1,1,1] neg_lo:[1,0,0] neg_hi:[1,0,0]
	ds_write2st64_b32 v9, v14, v15 offset0:0 offset1:4
	s_waitcnt lgkmcnt(6)
	v_pk_mul_f32 v[10:11], v[2:3], v[68:69] op_sel_hi:[0,1]
	ds_read_b128 v[20:23], v6 offset:4608
	v_pk_fma_f32 v[14:15], v[2:3], v[72:73], v[106:107] op_sel_hi:[0,1,1]
	v_pk_fma_f32 v[10:11], v[2:3], v[70:71], v[10:11] op_sel:[1,0,0] op_sel_hi:[1,1,1]
	ds_read_b128 v[24:27], v6 offset:4864
	v_pk_fma_f32 v[14:15], v[2:3], v[74:75], v[14:15] op_sel:[1,0,0] op_sel_hi:[1,1,1]
	v_pk_fma_f32 v[10:11], v[4:5], v[76:77], v[10:11] op_sel_hi:[0,1,1]
	v_pk_fma_f32 v[14:15], v[4:5], v[80:81], v[14:15] op_sel_hi:[0,1,1]
	ds_read_b128 v[56:59], v7 offset:512
	v_pk_fma_f32 v[10:11], v[4:5], v[78:79], v[10:11] op_sel:[1,0,0] op_sel_hi:[1,1,1]
	s_waitcnt lgkmcnt(7)
	v_pk_mul_f32 v[114:115], v[2:3], v[84:85]
	ds_read_b128 v[28:31], v6 offset:5120
	v_pk_mul_f32 v[116:117], v[4:5], v[86:87]
	v_add_f32_dpp v10, v10, v10 row_ror:8 row_mask:0xf bank_mask:0xf bound_ctrl:1
	v_add_f32_dpp v11, v11, v11 row_ror:8 row_mask:0xf bank_mask:0xf bound_ctrl:1
	ds_read_b128 v[32:35], v6 offset:5376
	v_pk_fma_f32 v[14:15], v[4:5], v[82:83], v[14:15] op_sel:[1,0,0] op_sel_hi:[1,1,1]
	v_add_f32_dpp v10, v10, v10 row_ror:4 row_mask:0xf bank_mask:0xf bound_ctrl:1
	ds_read_b128 v[36:39], v6 offset:5632
	v_add_f32_dpp v11, v11, v11 row_ror:4 row_mask:0xf bank_mask:0xf bound_ctrl:1
	v_pk_fma_f32 v[114:115], v[88:89], v[104:105], v[114:115] op_sel_hi:[1,0,1]
	v_add_f32_dpp v10, v10, v10 row_ror:2 row_mask:0xf bank_mask:0xf bound_ctrl:1
	ds_read_b128 v[40:43], v6 offset:5888
	v_add_f32_dpp v11, v11, v11 row_ror:2 row_mask:0xf bank_mask:0xf bound_ctrl:1
	v_pk_fma_f32 v[116:117], v[90:91], v[104:105], v[116:117] op_sel_hi:[1,0,1]
	ds_read_b128 v[48:51], v6 offset:6400
	v_add_f32_dpp v10, v10, v10 row_ror:1 row_mask:0xf bank_mask:0xf bound_ctrl:1
	v_add_f32_dpp v11, v11, v11 row_ror:1 row_mask:0xf bank_mask:0xf bound_ctrl:1
	s_waitcnt lgkmcnt(9)
	v_pk_fma_f32 v[114:115], v[96:97], v[104:105], v[114:115] op_sel:[0,1,0] op_sel_hi:[1,1,1]
	ds_read_b128 v[44:47], v6 offset:6144
	v_pk_fma_f32 v[116:117], v[98:99], v[104:105], v[116:117] op_sel:[0,1,0] op_sel_hi:[1,1,1]
	v_pk_fma_f32 v[114:115], v[92:93], v[10:11], v[114:115] op_sel_hi:[1,0,1] neg_lo:[1,0,0] neg_hi:[1,0,0]
	ds_read_b128 v[52:55], v6 offset:6656
	v_pk_fma_f32 v[116:117], v[94:95], v[10:11], v[116:117] op_sel_hi:[1,0,1] neg_lo:[1,0,0] neg_hi:[1,0,0]
	v_pk_fma_f32 v[2:3], v[100:101], v[10:11], v[114:115] op_sel:[0,1,0] op_sel_hi:[1,1,1] neg_lo:[1,0,0] neg_hi:[1,0,0]
	v_pk_fma_f32 v[4:5], v[102:103], v[10:11], v[116:117] op_sel:[0,1,0] op_sel_hi:[1,1,1] neg_lo:[1,0,0] neg_hi:[1,0,0]
	ds_write2st64_b32 v9, v14, v15 offset0:8 offset1:12
	s_waitcnt lgkmcnt(6)
	v_pk_mul_f32 v[10:11], v[2:3], v[20:21] op_sel_hi:[0,1]
	ds_read_b128 v[68:71], v6 offset:6912
	v_pk_fma_f32 v[14:15], v[2:3], v[24:25], v[58:59] op_sel_hi:[0,1,1]
	v_pk_fma_f32 v[10:11], v[2:3], v[22:23], v[10:11] op_sel:[1,0,0] op_sel_hi:[1,1,1]
	ds_read_b128 v[72:75], v6 offset:7168
	v_pk_fma_f32 v[14:15], v[2:3], v[26:27], v[14:15] op_sel:[1,0,0] op_sel_hi:[1,1,1]
	v_pk_fma_f32 v[10:11], v[4:5], v[28:29], v[10:11] op_sel_hi:[0,1,1]
	v_pk_fma_f32 v[14:15], v[4:5], v[32:33], v[14:15] op_sel_hi:[0,1,1]
	ds_read_b128 v[104:107], v7 offset:768
	v_pk_fma_f32 v[10:11], v[4:5], v[30:31], v[10:11] op_sel:[1,0,0] op_sel_hi:[1,1,1]
	s_waitcnt lgkmcnt(7)
	v_pk_mul_f32 v[114:115], v[2:3], v[36:37]
	ds_read_b128 v[76:79], v6 offset:7424
	v_pk_mul_f32 v[116:117], v[4:5], v[38:39]
	v_add_f32_dpp v10, v10, v10 row_ror:8 row_mask:0xf bank_mask:0xf bound_ctrl:1
	v_add_f32_dpp v11, v11, v11 row_ror:8 row_mask:0xf bank_mask:0xf bound_ctrl:1
	ds_read_b128 v[80:83], v6 offset:7680
	v_pk_fma_f32 v[14:15], v[4:5], v[34:35], v[14:15] op_sel:[1,0,0] op_sel_hi:[1,1,1]
	v_add_f32_dpp v10, v10, v10 row_ror:4 row_mask:0xf bank_mask:0xf bound_ctrl:1
	ds_read_b128 v[84:87], v6 offset:7936
	v_add_f32_dpp v11, v11, v11 row_ror:4 row_mask:0xf bank_mask:0xf bound_ctrl:1
	v_pk_fma_f32 v[114:115], v[40:41], v[56:57], v[114:115] op_sel_hi:[1,0,1]
	v_add_f32_dpp v10, v10, v10 row_ror:2 row_mask:0xf bank_mask:0xf bound_ctrl:1
	ds_read_b128 v[88:91], v6 offset:8192
	v_add_f32_dpp v11, v11, v11 row_ror:2 row_mask:0xf bank_mask:0xf bound_ctrl:1
	v_pk_fma_f32 v[116:117], v[42:43], v[56:57], v[116:117] op_sel_hi:[1,0,1]
	ds_read_b128 v[96:99], v6 offset:8704
	v_add_f32_dpp v10, v10, v10 row_ror:1 row_mask:0xf bank_mask:0xf bound_ctrl:1
	v_add_f32_dpp v11, v11, v11 row_ror:1 row_mask:0xf bank_mask:0xf bound_ctrl:1
	s_waitcnt lgkmcnt(9)
	v_pk_fma_f32 v[114:115], v[48:49], v[56:57], v[114:115] op_sel:[0,1,0] op_sel_hi:[1,1,1]
	ds_read_b128 v[92:95], v6 offset:8448
	v_pk_fma_f32 v[116:117], v[50:51], v[56:57], v[116:117] op_sel:[0,1,0] op_sel_hi:[1,1,1]
	v_pk_fma_f32 v[114:115], v[44:45], v[10:11], v[114:115] op_sel_hi:[1,0,1] neg_lo:[1,0,0] neg_hi:[1,0,0]
	ds_read_b128 v[100:103], v6 offset:8960
	v_pk_fma_f32 v[116:117], v[46:47], v[10:11], v[116:117] op_sel_hi:[1,0,1] neg_lo:[1,0,0] neg_hi:[1,0,0]
	v_pk_fma_f32 v[2:3], v[52:53], v[10:11], v[114:115] op_sel:[0,1,0] op_sel_hi:[1,1,1] neg_lo:[1,0,0] neg_hi:[1,0,0]
	v_pk_fma_f32 v[4:5], v[54:55], v[10:11], v[116:117] op_sel:[0,1,0] op_sel_hi:[1,1,1] neg_lo:[1,0,0] neg_hi:[1,0,0]
	ds_write2st64_b32 v9, v14, v15 offset0:16 offset1:20
	s_waitcnt lgkmcnt(6)
	v_pk_mul_f32 v[10:11], v[2:3], v[68:69] op_sel_hi:[0,1]
	ds_read_b128 v[20:23], v6 offset:9216
	v_pk_fma_f32 v[14:15], v[2:3], v[72:73], v[106:107] op_sel_hi:[0,1,1]
	v_pk_fma_f32 v[10:11], v[2:3], v[70:71], v[10:11] op_sel:[1,0,0] op_sel_hi:[1,1,1]
	ds_read_b128 v[24:27], v6 offset:9472
	v_pk_fma_f32 v[14:15], v[2:3], v[74:75], v[14:15] op_sel:[1,0,0] op_sel_hi:[1,1,1]
	v_pk_fma_f32 v[10:11], v[4:5], v[76:77], v[10:11] op_sel_hi:[0,1,1]
	v_pk_fma_f32 v[14:15], v[4:5], v[80:81], v[14:15] op_sel_hi:[0,1,1]
	ds_read_b128 v[56:59], v7 offset:1024
	v_pk_fma_f32 v[10:11], v[4:5], v[78:79], v[10:11] op_sel:[1,0,0] op_sel_hi:[1,1,1]
	s_waitcnt lgkmcnt(7)
	v_pk_mul_f32 v[114:115], v[2:3], v[84:85]
	ds_read_b128 v[28:31], v6 offset:9728
	v_pk_mul_f32 v[116:117], v[4:5], v[86:87]
	v_add_f32_dpp v10, v10, v10 row_ror:8 row_mask:0xf bank_mask:0xf bound_ctrl:1
	v_add_f32_dpp v11, v11, v11 row_ror:8 row_mask:0xf bank_mask:0xf bound_ctrl:1
	ds_read_b128 v[32:35], v6 offset:9984
	v_pk_fma_f32 v[14:15], v[4:5], v[82:83], v[14:15] op_sel:[1,0,0] op_sel_hi:[1,1,1]
	v_add_f32_dpp v10, v10, v10 row_ror:4 row_mask:0xf bank_mask:0xf bound_ctrl:1
	ds_read_b128 v[36:39], v6 offset:10240
	v_add_f32_dpp v11, v11, v11 row_ror:4 row_mask:0xf bank_mask:0xf bound_ctrl:1
	v_pk_fma_f32 v[114:115], v[88:89], v[104:105], v[114:115] op_sel_hi:[1,0,1]
	v_add_f32_dpp v10, v10, v10 row_ror:2 row_mask:0xf bank_mask:0xf bound_ctrl:1
	ds_read_b128 v[40:43], v6 offset:10496
	v_add_f32_dpp v11, v11, v11 row_ror:2 row_mask:0xf bank_mask:0xf bound_ctrl:1
	v_pk_fma_f32 v[116:117], v[90:91], v[104:105], v[116:117] op_sel_hi:[1,0,1]
	ds_read_b128 v[48:51], v6 offset:11008
	v_add_f32_dpp v10, v10, v10 row_ror:1 row_mask:0xf bank_mask:0xf bound_ctrl:1
	v_add_f32_dpp v11, v11, v11 row_ror:1 row_mask:0xf bank_mask:0xf bound_ctrl:1
	s_waitcnt lgkmcnt(9)
	v_pk_fma_f32 v[114:115], v[96:97], v[104:105], v[114:115] op_sel:[0,1,0] op_sel_hi:[1,1,1]
	ds_read_b128 v[44:47], v6 offset:10752
	v_pk_fma_f32 v[116:117], v[98:99], v[104:105], v[116:117] op_sel:[0,1,0] op_sel_hi:[1,1,1]
	v_pk_fma_f32 v[114:115], v[92:93], v[10:11], v[114:115] op_sel_hi:[1,0,1] neg_lo:[1,0,0] neg_hi:[1,0,0]
	ds_read_b128 v[52:55], v6 offset:11264
	v_pk_fma_f32 v[116:117], v[94:95], v[10:11], v[116:117] op_sel_hi:[1,0,1] neg_lo:[1,0,0] neg_hi:[1,0,0]
	v_pk_fma_f32 v[2:3], v[100:101], v[10:11], v[114:115] op_sel:[0,1,0] op_sel_hi:[1,1,1] neg_lo:[1,0,0] neg_hi:[1,0,0]
	v_pk_fma_f32 v[4:5], v[102:103], v[10:11], v[116:117] op_sel:[0,1,0] op_sel_hi:[1,1,1] neg_lo:[1,0,0] neg_hi:[1,0,0]
	ds_write2st64_b32 v9, v14, v15 offset0:24 offset1:28
	s_waitcnt lgkmcnt(6)
	v_pk_mul_f32 v[10:11], v[2:3], v[20:21] op_sel_hi:[0,1]
	ds_read_b128 v[68:71], v6 offset:11520
	v_pk_fma_f32 v[14:15], v[2:3], v[24:25], v[58:59] op_sel_hi:[0,1,1]
	v_pk_fma_f32 v[10:11], v[2:3], v[22:23], v[10:11] op_sel:[1,0,0] op_sel_hi:[1,1,1]
	ds_read_b128 v[72:75], v6 offset:11776
	v_pk_fma_f32 v[14:15], v[2:3], v[26:27], v[14:15] op_sel:[1,0,0] op_sel_hi:[1,1,1]
	v_pk_fma_f32 v[10:11], v[4:5], v[28:29], v[10:11] op_sel_hi:[0,1,1]
	v_pk_fma_f32 v[14:15], v[4:5], v[32:33], v[14:15] op_sel_hi:[0,1,1]
	ds_read_b128 v[104:107], v7 offset:1280
	v_pk_fma_f32 v[10:11], v[4:5], v[30:31], v[10:11] op_sel:[1,0,0] op_sel_hi:[1,1,1]
	s_waitcnt lgkmcnt(7)
	v_pk_mul_f32 v[114:115], v[2:3], v[36:37]
	ds_read_b128 v[76:79], v6 offset:12032
	v_pk_mul_f32 v[116:117], v[4:5], v[38:39]
	v_add_f32_dpp v10, v10, v10 row_ror:8 row_mask:0xf bank_mask:0xf bound_ctrl:1
	v_add_f32_dpp v11, v11, v11 row_ror:8 row_mask:0xf bank_mask:0xf bound_ctrl:1
	ds_read_b128 v[80:83], v6 offset:12288
	v_pk_fma_f32 v[14:15], v[4:5], v[34:35], v[14:15] op_sel:[1,0,0] op_sel_hi:[1,1,1]
	v_add_f32_dpp v10, v10, v10 row_ror:4 row_mask:0xf bank_mask:0xf bound_ctrl:1
	ds_read_b128 v[84:87], v6 offset:12544
	v_add_f32_dpp v11, v11, v11 row_ror:4 row_mask:0xf bank_mask:0xf bound_ctrl:1
	v_pk_fma_f32 v[114:115], v[40:41], v[56:57], v[114:115] op_sel_hi:[1,0,1]
	v_add_f32_dpp v10, v10, v10 row_ror:2 row_mask:0xf bank_mask:0xf bound_ctrl:1
	ds_read_b128 v[88:91], v6 offset:12800
	v_add_f32_dpp v11, v11, v11 row_ror:2 row_mask:0xf bank_mask:0xf bound_ctrl:1
	v_pk_fma_f32 v[116:117], v[42:43], v[56:57], v[116:117] op_sel_hi:[1,0,1]
	ds_read_b128 v[96:99], v6 offset:13312
	v_add_f32_dpp v10, v10, v10 row_ror:1 row_mask:0xf bank_mask:0xf bound_ctrl:1
	v_add_f32_dpp v11, v11, v11 row_ror:1 row_mask:0xf bank_mask:0xf bound_ctrl:1
	s_waitcnt lgkmcnt(9)
	v_pk_fma_f32 v[114:115], v[48:49], v[56:57], v[114:115] op_sel:[0,1,0] op_sel_hi:[1,1,1]
	ds_read_b128 v[92:95], v6 offset:13056
	v_pk_fma_f32 v[116:117], v[50:51], v[56:57], v[116:117] op_sel:[0,1,0] op_sel_hi:[1,1,1]
	v_pk_fma_f32 v[114:115], v[44:45], v[10:11], v[114:115] op_sel_hi:[1,0,1] neg_lo:[1,0,0] neg_hi:[1,0,0]
	ds_read_b128 v[100:103], v6 offset:13568
	v_pk_fma_f32 v[116:117], v[46:47], v[10:11], v[116:117] op_sel_hi:[1,0,1] neg_lo:[1,0,0] neg_hi:[1,0,0]
	v_pk_fma_f32 v[2:3], v[52:53], v[10:11], v[114:115] op_sel:[0,1,0] op_sel_hi:[1,1,1] neg_lo:[1,0,0] neg_hi:[1,0,0]
	v_pk_fma_f32 v[4:5], v[54:55], v[10:11], v[116:117] op_sel:[0,1,0] op_sel_hi:[1,1,1] neg_lo:[1,0,0] neg_hi:[1,0,0]
	ds_write2st64_b32 v9, v14, v15 offset0:32 offset1:36
	s_waitcnt lgkmcnt(6)
	v_pk_mul_f32 v[10:11], v[2:3], v[68:69] op_sel_hi:[0,1]
	ds_read_b128 v[20:23], v6 offset:13824
	v_pk_fma_f32 v[14:15], v[2:3], v[72:73], v[106:107] op_sel_hi:[0,1,1]
	v_pk_fma_f32 v[10:11], v[2:3], v[70:71], v[10:11] op_sel:[1,0,0] op_sel_hi:[1,1,1]
	ds_read_b128 v[24:27], v6 offset:14080
	v_pk_fma_f32 v[14:15], v[2:3], v[74:75], v[14:15] op_sel:[1,0,0] op_sel_hi:[1,1,1]
	v_pk_fma_f32 v[10:11], v[4:5], v[76:77], v[10:11] op_sel_hi:[0,1,1]
	v_pk_fma_f32 v[14:15], v[4:5], v[80:81], v[14:15] op_sel_hi:[0,1,1]
	ds_read_b128 v[56:59], v7 offset:1536
	v_pk_fma_f32 v[10:11], v[4:5], v[78:79], v[10:11] op_sel:[1,0,0] op_sel_hi:[1,1,1]
	s_waitcnt lgkmcnt(7)
	v_pk_mul_f32 v[114:115], v[2:3], v[84:85]
	ds_read_b128 v[28:31], v6 offset:14336
	v_pk_mul_f32 v[116:117], v[4:5], v[86:87]
	v_add_f32_dpp v10, v10, v10 row_ror:8 row_mask:0xf bank_mask:0xf bound_ctrl:1
	v_add_f32_dpp v11, v11, v11 row_ror:8 row_mask:0xf bank_mask:0xf bound_ctrl:1
	ds_read_b128 v[32:35], v6 offset:14592
	v_pk_fma_f32 v[14:15], v[4:5], v[82:83], v[14:15] op_sel:[1,0,0] op_sel_hi:[1,1,1]
	v_add_f32_dpp v10, v10, v10 row_ror:4 row_mask:0xf bank_mask:0xf bound_ctrl:1
	ds_read_b128 v[36:39], v6 offset:14848
	v_add_f32_dpp v11, v11, v11 row_ror:4 row_mask:0xf bank_mask:0xf bound_ctrl:1
	v_pk_fma_f32 v[114:115], v[88:89], v[104:105], v[114:115] op_sel_hi:[1,0,1]
	v_add_f32_dpp v10, v10, v10 row_ror:2 row_mask:0xf bank_mask:0xf bound_ctrl:1
	ds_read_b128 v[40:43], v6 offset:15104
	v_add_f32_dpp v11, v11, v11 row_ror:2 row_mask:0xf bank_mask:0xf bound_ctrl:1
	v_pk_fma_f32 v[116:117], v[90:91], v[104:105], v[116:117] op_sel_hi:[1,0,1]
	ds_read_b128 v[48:51], v6 offset:15616
	v_add_f32_dpp v10, v10, v10 row_ror:1 row_mask:0xf bank_mask:0xf bound_ctrl:1
	v_add_f32_dpp v11, v11, v11 row_ror:1 row_mask:0xf bank_mask:0xf bound_ctrl:1
	s_waitcnt lgkmcnt(9)
	v_pk_fma_f32 v[114:115], v[96:97], v[104:105], v[114:115] op_sel:[0,1,0] op_sel_hi:[1,1,1]
	ds_read_b128 v[44:47], v6 offset:15360
	v_pk_fma_f32 v[116:117], v[98:99], v[104:105], v[116:117] op_sel:[0,1,0] op_sel_hi:[1,1,1]
	v_pk_fma_f32 v[114:115], v[92:93], v[10:11], v[114:115] op_sel_hi:[1,0,1] neg_lo:[1,0,0] neg_hi:[1,0,0]
	ds_read_b128 v[52:55], v6 offset:15872
	v_pk_fma_f32 v[116:117], v[94:95], v[10:11], v[116:117] op_sel_hi:[1,0,1] neg_lo:[1,0,0] neg_hi:[1,0,0]
	v_pk_fma_f32 v[2:3], v[100:101], v[10:11], v[114:115] op_sel:[0,1,0] op_sel_hi:[1,1,1] neg_lo:[1,0,0] neg_hi:[1,0,0]
	v_pk_fma_f32 v[4:5], v[102:103], v[10:11], v[116:117] op_sel:[0,1,0] op_sel_hi:[1,1,1] neg_lo:[1,0,0] neg_hi:[1,0,0]
	ds_write2st64_b32 v9, v14, v15 offset0:40 offset1:44
	s_waitcnt lgkmcnt(6)
	v_pk_mul_f32 v[10:11], v[2:3], v[20:21] op_sel_hi:[0,1]
	ds_read_b128 v[68:71], v6 offset:16128
	v_pk_fma_f32 v[14:15], v[2:3], v[24:25], v[58:59] op_sel_hi:[0,1,1]
	v_pk_fma_f32 v[10:11], v[2:3], v[22:23], v[10:11] op_sel:[1,0,0] op_sel_hi:[1,1,1]
	ds_read_b128 v[72:75], v6 offset:16384
	v_pk_fma_f32 v[14:15], v[2:3], v[26:27], v[14:15] op_sel:[1,0,0] op_sel_hi:[1,1,1]
	v_pk_fma_f32 v[10:11], v[4:5], v[28:29], v[10:11] op_sel_hi:[0,1,1]
	v_pk_fma_f32 v[14:15], v[4:5], v[32:33], v[14:15] op_sel_hi:[0,1,1]
	ds_read_b128 v[104:107], v7 offset:1792
	v_pk_fma_f32 v[10:11], v[4:5], v[30:31], v[10:11] op_sel:[1,0,0] op_sel_hi:[1,1,1]
	s_waitcnt lgkmcnt(7)
	v_pk_mul_f32 v[114:115], v[2:3], v[36:37]
	ds_read_b128 v[76:79], v6 offset:16640
	v_pk_mul_f32 v[116:117], v[4:5], v[38:39]
	v_add_f32_dpp v10, v10, v10 row_ror:8 row_mask:0xf bank_mask:0xf bound_ctrl:1
	v_add_f32_dpp v11, v11, v11 row_ror:8 row_mask:0xf bank_mask:0xf bound_ctrl:1
	ds_read_b128 v[80:83], v6 offset:16896
	v_pk_fma_f32 v[14:15], v[4:5], v[34:35], v[14:15] op_sel:[1,0,0] op_sel_hi:[1,1,1]
	v_add_f32_dpp v10, v10, v10 row_ror:4 row_mask:0xf bank_mask:0xf bound_ctrl:1
	ds_read_b128 v[84:87], v6 offset:17152
	v_add_f32_dpp v11, v11, v11 row_ror:4 row_mask:0xf bank_mask:0xf bound_ctrl:1
	v_pk_fma_f32 v[114:115], v[40:41], v[56:57], v[114:115] op_sel_hi:[1,0,1]
	v_add_f32_dpp v10, v10, v10 row_ror:2 row_mask:0xf bank_mask:0xf bound_ctrl:1
	ds_read_b128 v[88:91], v6 offset:17408
	v_add_f32_dpp v11, v11, v11 row_ror:2 row_mask:0xf bank_mask:0xf bound_ctrl:1
	v_pk_fma_f32 v[116:117], v[42:43], v[56:57], v[116:117] op_sel_hi:[1,0,1]
	ds_read_b128 v[96:99], v6 offset:17920
	v_add_f32_dpp v10, v10, v10 row_ror:1 row_mask:0xf bank_mask:0xf bound_ctrl:1
	v_add_f32_dpp v11, v11, v11 row_ror:1 row_mask:0xf bank_mask:0xf bound_ctrl:1
	s_waitcnt lgkmcnt(9)
	v_pk_fma_f32 v[114:115], v[48:49], v[56:57], v[114:115] op_sel:[0,1,0] op_sel_hi:[1,1,1]
	ds_read_b128 v[92:95], v6 offset:17664
	v_pk_fma_f32 v[116:117], v[50:51], v[56:57], v[116:117] op_sel:[0,1,0] op_sel_hi:[1,1,1]
	v_pk_fma_f32 v[114:115], v[44:45], v[10:11], v[114:115] op_sel_hi:[1,0,1] neg_lo:[1,0,0] neg_hi:[1,0,0]
	ds_read_b128 v[100:103], v6 offset:18176
	v_pk_fma_f32 v[116:117], v[46:47], v[10:11], v[116:117] op_sel_hi:[1,0,1] neg_lo:[1,0,0] neg_hi:[1,0,0]
	v_pk_fma_f32 v[2:3], v[52:53], v[10:11], v[114:115] op_sel:[0,1,0] op_sel_hi:[1,1,1] neg_lo:[1,0,0] neg_hi:[1,0,0]
	v_pk_fma_f32 v[4:5], v[54:55], v[10:11], v[116:117] op_sel:[0,1,0] op_sel_hi:[1,1,1] neg_lo:[1,0,0] neg_hi:[1,0,0]
	ds_write2st64_b32 v9, v14, v15 offset0:48 offset1:52
	s_waitcnt lgkmcnt(6)
	v_pk_mul_f32 v[10:11], v[2:3], v[68:69] op_sel_hi:[0,1]
	ds_read_b128 v[20:23], v6 offset:18432
	v_pk_fma_f32 v[14:15], v[2:3], v[72:73], v[106:107] op_sel_hi:[0,1,1]
	v_pk_fma_f32 v[10:11], v[2:3], v[70:71], v[10:11] op_sel:[1,0,0] op_sel_hi:[1,1,1]
	ds_read_b128 v[24:27], v6 offset:18688
	v_pk_fma_f32 v[14:15], v[2:3], v[74:75], v[14:15] op_sel:[1,0,0] op_sel_hi:[1,1,1]
	v_pk_fma_f32 v[10:11], v[4:5], v[76:77], v[10:11] op_sel_hi:[0,1,1]
	v_pk_fma_f32 v[14:15], v[4:5], v[80:81], v[14:15] op_sel_hi:[0,1,1]
	ds_read_b128 v[56:59], v7 offset:2048
	v_pk_fma_f32 v[10:11], v[4:5], v[78:79], v[10:11] op_sel:[1,0,0] op_sel_hi:[1,1,1]
	s_waitcnt lgkmcnt(7)
	v_pk_mul_f32 v[114:115], v[2:3], v[84:85]
	ds_read_b128 v[28:31], v6 offset:18944
	v_pk_mul_f32 v[116:117], v[4:5], v[86:87]
	v_add_f32_dpp v10, v10, v10 row_ror:8 row_mask:0xf bank_mask:0xf bound_ctrl:1
	v_add_f32_dpp v11, v11, v11 row_ror:8 row_mask:0xf bank_mask:0xf bound_ctrl:1
	ds_read_b128 v[32:35], v6 offset:19200
	v_pk_fma_f32 v[14:15], v[4:5], v[82:83], v[14:15] op_sel:[1,0,0] op_sel_hi:[1,1,1]
	v_add_f32_dpp v10, v10, v10 row_ror:4 row_mask:0xf bank_mask:0xf bound_ctrl:1
	ds_read_b128 v[36:39], v6 offset:19456
	v_add_f32_dpp v11, v11, v11 row_ror:4 row_mask:0xf bank_mask:0xf bound_ctrl:1
	v_pk_fma_f32 v[114:115], v[88:89], v[104:105], v[114:115] op_sel_hi:[1,0,1]
	v_add_f32_dpp v10, v10, v10 row_ror:2 row_mask:0xf bank_mask:0xf bound_ctrl:1
	ds_read_b128 v[40:43], v6 offset:19712
	v_add_f32_dpp v11, v11, v11 row_ror:2 row_mask:0xf bank_mask:0xf bound_ctrl:1
	v_pk_fma_f32 v[116:117], v[90:91], v[104:105], v[116:117] op_sel_hi:[1,0,1]
	ds_read_b128 v[48:51], v6 offset:20224
	v_add_f32_dpp v10, v10, v10 row_ror:1 row_mask:0xf bank_mask:0xf bound_ctrl:1
	v_add_f32_dpp v11, v11, v11 row_ror:1 row_mask:0xf bank_mask:0xf bound_ctrl:1
	s_waitcnt lgkmcnt(9)
	v_pk_fma_f32 v[114:115], v[96:97], v[104:105], v[114:115] op_sel:[0,1,0] op_sel_hi:[1,1,1]
	ds_read_b128 v[44:47], v6 offset:19968
	v_pk_fma_f32 v[116:117], v[98:99], v[104:105], v[116:117] op_sel:[0,1,0] op_sel_hi:[1,1,1]
	v_pk_fma_f32 v[114:115], v[92:93], v[10:11], v[114:115] op_sel_hi:[1,0,1] neg_lo:[1,0,0] neg_hi:[1,0,0]
	ds_read_b128 v[52:55], v6 offset:20480
	v_pk_fma_f32 v[116:117], v[94:95], v[10:11], v[116:117] op_sel_hi:[1,0,1] neg_lo:[1,0,0] neg_hi:[1,0,0]
	v_pk_fma_f32 v[2:3], v[100:101], v[10:11], v[114:115] op_sel:[0,1,0] op_sel_hi:[1,1,1] neg_lo:[1,0,0] neg_hi:[1,0,0]
	v_pk_fma_f32 v[4:5], v[102:103], v[10:11], v[116:117] op_sel:[0,1,0] op_sel_hi:[1,1,1] neg_lo:[1,0,0] neg_hi:[1,0,0]
	ds_write2st64_b32 v9, v14, v15 offset0:56 offset1:60
	s_waitcnt lgkmcnt(6)
	v_pk_mul_f32 v[10:11], v[2:3], v[20:21] op_sel_hi:[0,1]
	ds_read_b128 v[68:71], v6 offset:20736
	v_pk_fma_f32 v[14:15], v[2:3], v[24:25], v[58:59] op_sel_hi:[0,1,1]
	v_pk_fma_f32 v[10:11], v[2:3], v[22:23], v[10:11] op_sel:[1,0,0] op_sel_hi:[1,1,1]
	ds_read_b128 v[72:75], v6 offset:20992
	v_pk_fma_f32 v[14:15], v[2:3], v[26:27], v[14:15] op_sel:[1,0,0] op_sel_hi:[1,1,1]
	v_pk_fma_f32 v[10:11], v[4:5], v[28:29], v[10:11] op_sel_hi:[0,1,1]
	v_pk_fma_f32 v[14:15], v[4:5], v[32:33], v[14:15] op_sel_hi:[0,1,1]
	ds_read_b128 v[104:107], v7 offset:2304
	v_pk_fma_f32 v[10:11], v[4:5], v[30:31], v[10:11] op_sel:[1,0,0] op_sel_hi:[1,1,1]
	s_waitcnt lgkmcnt(7)
	v_pk_mul_f32 v[114:115], v[2:3], v[36:37]
	ds_read_b128 v[76:79], v6 offset:21248
	v_pk_mul_f32 v[116:117], v[4:5], v[38:39]
	v_add_f32_dpp v10, v10, v10 row_ror:8 row_mask:0xf bank_mask:0xf bound_ctrl:1
	v_add_f32_dpp v11, v11, v11 row_ror:8 row_mask:0xf bank_mask:0xf bound_ctrl:1
	ds_read_b128 v[80:83], v6 offset:21504
	v_pk_fma_f32 v[14:15], v[4:5], v[34:35], v[14:15] op_sel:[1,0,0] op_sel_hi:[1,1,1]
	v_add_f32_dpp v10, v10, v10 row_ror:4 row_mask:0xf bank_mask:0xf bound_ctrl:1
	ds_read_b128 v[84:87], v6 offset:21760
	v_add_f32_dpp v11, v11, v11 row_ror:4 row_mask:0xf bank_mask:0xf bound_ctrl:1
	v_pk_fma_f32 v[114:115], v[40:41], v[56:57], v[114:115] op_sel_hi:[1,0,1]
	v_add_f32_dpp v10, v10, v10 row_ror:2 row_mask:0xf bank_mask:0xf bound_ctrl:1
	ds_read_b128 v[88:91], v6 offset:22016
	v_add_f32_dpp v11, v11, v11 row_ror:2 row_mask:0xf bank_mask:0xf bound_ctrl:1
	v_pk_fma_f32 v[116:117], v[42:43], v[56:57], v[116:117] op_sel_hi:[1,0,1]
	ds_read_b128 v[96:99], v6 offset:22528
	v_add_f32_dpp v10, v10, v10 row_ror:1 row_mask:0xf bank_mask:0xf bound_ctrl:1
	v_add_f32_dpp v11, v11, v11 row_ror:1 row_mask:0xf bank_mask:0xf bound_ctrl:1
	s_waitcnt lgkmcnt(9)
	v_pk_fma_f32 v[114:115], v[48:49], v[56:57], v[114:115] op_sel:[0,1,0] op_sel_hi:[1,1,1]
	ds_read_b128 v[92:95], v6 offset:22272
	v_pk_fma_f32 v[116:117], v[50:51], v[56:57], v[116:117] op_sel:[0,1,0] op_sel_hi:[1,1,1]
	v_pk_fma_f32 v[114:115], v[44:45], v[10:11], v[114:115] op_sel_hi:[1,0,1] neg_lo:[1,0,0] neg_hi:[1,0,0]
	ds_read_b128 v[100:103], v6 offset:22784
	v_pk_fma_f32 v[116:117], v[46:47], v[10:11], v[116:117] op_sel_hi:[1,0,1] neg_lo:[1,0,0] neg_hi:[1,0,0]
	v_pk_fma_f32 v[2:3], v[52:53], v[10:11], v[114:115] op_sel:[0,1,0] op_sel_hi:[1,1,1] neg_lo:[1,0,0] neg_hi:[1,0,0]
	v_pk_fma_f32 v[4:5], v[54:55], v[10:11], v[116:117] op_sel:[0,1,0] op_sel_hi:[1,1,1] neg_lo:[1,0,0] neg_hi:[1,0,0]
	ds_write2st64_b32 v9, v14, v15 offset0:64 offset1:68
	s_waitcnt lgkmcnt(6)
	v_pk_mul_f32 v[10:11], v[2:3], v[68:69] op_sel_hi:[0,1]
	ds_read_b128 v[20:23], v6 offset:23040
	v_pk_fma_f32 v[14:15], v[2:3], v[72:73], v[106:107] op_sel_hi:[0,1,1]
	v_pk_fma_f32 v[10:11], v[2:3], v[70:71], v[10:11] op_sel:[1,0,0] op_sel_hi:[1,1,1]
	ds_read_b128 v[24:27], v6 offset:23296
	v_pk_fma_f32 v[14:15], v[2:3], v[74:75], v[14:15] op_sel:[1,0,0] op_sel_hi:[1,1,1]
	v_pk_fma_f32 v[10:11], v[4:5], v[76:77], v[10:11] op_sel_hi:[0,1,1]
	v_pk_fma_f32 v[14:15], v[4:5], v[80:81], v[14:15] op_sel_hi:[0,1,1]
	ds_read_b128 v[56:59], v7 offset:2560
	v_pk_fma_f32 v[10:11], v[4:5], v[78:79], v[10:11] op_sel:[1,0,0] op_sel_hi:[1,1,1]
	s_waitcnt lgkmcnt(7)
	v_pk_mul_f32 v[114:115], v[2:3], v[84:85]
	ds_read_b128 v[28:31], v6 offset:23552
	v_pk_mul_f32 v[116:117], v[4:5], v[86:87]
	v_add_f32_dpp v10, v10, v10 row_ror:8 row_mask:0xf bank_mask:0xf bound_ctrl:1
	v_add_f32_dpp v11, v11, v11 row_ror:8 row_mask:0xf bank_mask:0xf bound_ctrl:1
	ds_read_b128 v[32:35], v6 offset:23808
	v_pk_fma_f32 v[14:15], v[4:5], v[82:83], v[14:15] op_sel:[1,0,0] op_sel_hi:[1,1,1]
	v_add_f32_dpp v10, v10, v10 row_ror:4 row_mask:0xf bank_mask:0xf bound_ctrl:1
	ds_read_b128 v[36:39], v6 offset:24064
	v_add_f32_dpp v11, v11, v11 row_ror:4 row_mask:0xf bank_mask:0xf bound_ctrl:1
	v_pk_fma_f32 v[114:115], v[88:89], v[104:105], v[114:115] op_sel_hi:[1,0,1]
	v_add_f32_dpp v10, v10, v10 row_ror:2 row_mask:0xf bank_mask:0xf bound_ctrl:1
	ds_read_b128 v[40:43], v6 offset:24320
	v_add_f32_dpp v11, v11, v11 row_ror:2 row_mask:0xf bank_mask:0xf bound_ctrl:1
	v_pk_fma_f32 v[116:117], v[90:91], v[104:105], v[116:117] op_sel_hi:[1,0,1]
	ds_read_b128 v[48:51], v6 offset:24832
	v_add_f32_dpp v10, v10, v10 row_ror:1 row_mask:0xf bank_mask:0xf bound_ctrl:1
	v_add_f32_dpp v11, v11, v11 row_ror:1 row_mask:0xf bank_mask:0xf bound_ctrl:1
	s_waitcnt lgkmcnt(9)
	v_pk_fma_f32 v[114:115], v[96:97], v[104:105], v[114:115] op_sel:[0,1,0] op_sel_hi:[1,1,1]
	ds_read_b128 v[44:47], v6 offset:24576
	v_pk_fma_f32 v[116:117], v[98:99], v[104:105], v[116:117] op_sel:[0,1,0] op_sel_hi:[1,1,1]
	v_pk_fma_f32 v[114:115], v[92:93], v[10:11], v[114:115] op_sel_hi:[1,0,1] neg_lo:[1,0,0] neg_hi:[1,0,0]
	ds_read_b128 v[52:55], v6 offset:25088
	v_pk_fma_f32 v[116:117], v[94:95], v[10:11], v[116:117] op_sel_hi:[1,0,1] neg_lo:[1,0,0] neg_hi:[1,0,0]
	v_pk_fma_f32 v[2:3], v[100:101], v[10:11], v[114:115] op_sel:[0,1,0] op_sel_hi:[1,1,1] neg_lo:[1,0,0] neg_hi:[1,0,0]
	v_pk_fma_f32 v[4:5], v[102:103], v[10:11], v[116:117] op_sel:[0,1,0] op_sel_hi:[1,1,1] neg_lo:[1,0,0] neg_hi:[1,0,0]
	ds_write2st64_b32 v9, v14, v15 offset0:72 offset1:76
	s_waitcnt lgkmcnt(6)
	v_pk_mul_f32 v[10:11], v[2:3], v[20:21] op_sel_hi:[0,1]
	ds_read_b128 v[68:71], v6 offset:25344
	v_pk_fma_f32 v[14:15], v[2:3], v[24:25], v[58:59] op_sel_hi:[0,1,1]
	v_pk_fma_f32 v[10:11], v[2:3], v[22:23], v[10:11] op_sel:[1,0,0] op_sel_hi:[1,1,1]
	ds_read_b128 v[72:75], v6 offset:25600
	v_pk_fma_f32 v[14:15], v[2:3], v[26:27], v[14:15] op_sel:[1,0,0] op_sel_hi:[1,1,1]
	v_pk_fma_f32 v[10:11], v[4:5], v[28:29], v[10:11] op_sel_hi:[0,1,1]
	v_pk_fma_f32 v[14:15], v[4:5], v[32:33], v[14:15] op_sel_hi:[0,1,1]
	ds_read_b128 v[104:107], v7 offset:2816
	v_pk_fma_f32 v[10:11], v[4:5], v[30:31], v[10:11] op_sel:[1,0,0] op_sel_hi:[1,1,1]
	s_waitcnt lgkmcnt(7)
	v_pk_mul_f32 v[114:115], v[2:3], v[36:37]
	ds_read_b128 v[76:79], v6 offset:25856
	v_pk_mul_f32 v[116:117], v[4:5], v[38:39]
	v_add_f32_dpp v10, v10, v10 row_ror:8 row_mask:0xf bank_mask:0xf bound_ctrl:1
	v_add_f32_dpp v11, v11, v11 row_ror:8 row_mask:0xf bank_mask:0xf bound_ctrl:1
	ds_read_b128 v[80:83], v6 offset:26112
	v_pk_fma_f32 v[14:15], v[4:5], v[34:35], v[14:15] op_sel:[1,0,0] op_sel_hi:[1,1,1]
	v_add_f32_dpp v10, v10, v10 row_ror:4 row_mask:0xf bank_mask:0xf bound_ctrl:1
	ds_read_b128 v[84:87], v6 offset:26368
	v_add_f32_dpp v11, v11, v11 row_ror:4 row_mask:0xf bank_mask:0xf bound_ctrl:1
	v_pk_fma_f32 v[114:115], v[40:41], v[56:57], v[114:115] op_sel_hi:[1,0,1]
	v_add_f32_dpp v10, v10, v10 row_ror:2 row_mask:0xf bank_mask:0xf bound_ctrl:1
	ds_read_b128 v[88:91], v6 offset:26624
	v_add_f32_dpp v11, v11, v11 row_ror:2 row_mask:0xf bank_mask:0xf bound_ctrl:1
	v_pk_fma_f32 v[116:117], v[42:43], v[56:57], v[116:117] op_sel_hi:[1,0,1]
	ds_read_b128 v[96:99], v6 offset:27136
	v_add_f32_dpp v10, v10, v10 row_ror:1 row_mask:0xf bank_mask:0xf bound_ctrl:1
	v_add_f32_dpp v11, v11, v11 row_ror:1 row_mask:0xf bank_mask:0xf bound_ctrl:1
	s_waitcnt lgkmcnt(9)
	v_pk_fma_f32 v[114:115], v[48:49], v[56:57], v[114:115] op_sel:[0,1,0] op_sel_hi:[1,1,1]
	ds_read_b128 v[92:95], v6 offset:26880
	v_pk_fma_f32 v[116:117], v[50:51], v[56:57], v[116:117] op_sel:[0,1,0] op_sel_hi:[1,1,1]
	v_pk_fma_f32 v[114:115], v[44:45], v[10:11], v[114:115] op_sel_hi:[1,0,1] neg_lo:[1,0,0] neg_hi:[1,0,0]
	ds_read_b128 v[100:103], v6 offset:27392
	v_pk_fma_f32 v[116:117], v[46:47], v[10:11], v[116:117] op_sel_hi:[1,0,1] neg_lo:[1,0,0] neg_hi:[1,0,0]
	v_pk_fma_f32 v[2:3], v[52:53], v[10:11], v[114:115] op_sel:[0,1,0] op_sel_hi:[1,1,1] neg_lo:[1,0,0] neg_hi:[1,0,0]
	v_pk_fma_f32 v[4:5], v[54:55], v[10:11], v[116:117] op_sel:[0,1,0] op_sel_hi:[1,1,1] neg_lo:[1,0,0] neg_hi:[1,0,0]
	ds_write2st64_b32 v9, v14, v15 offset0:80 offset1:84
	s_waitcnt lgkmcnt(6)
	v_pk_mul_f32 v[10:11], v[2:3], v[68:69] op_sel_hi:[0,1]
	ds_read_b128 v[20:23], v6 offset:27648
	v_pk_fma_f32 v[14:15], v[2:3], v[72:73], v[106:107] op_sel_hi:[0,1,1]
	v_pk_fma_f32 v[10:11], v[2:3], v[70:71], v[10:11] op_sel:[1,0,0] op_sel_hi:[1,1,1]
	ds_read_b128 v[24:27], v6 offset:27904
	v_pk_fma_f32 v[14:15], v[2:3], v[74:75], v[14:15] op_sel:[1,0,0] op_sel_hi:[1,1,1]
	v_pk_fma_f32 v[10:11], v[4:5], v[76:77], v[10:11] op_sel_hi:[0,1,1]
	v_pk_fma_f32 v[14:15], v[4:5], v[80:81], v[14:15] op_sel_hi:[0,1,1]
	ds_read_b128 v[56:59], v7 offset:3072
	v_pk_fma_f32 v[10:11], v[4:5], v[78:79], v[10:11] op_sel:[1,0,0] op_sel_hi:[1,1,1]
	s_waitcnt lgkmcnt(7)
	v_pk_mul_f32 v[114:115], v[2:3], v[84:85]
	ds_read_b128 v[28:31], v6 offset:28160
	v_pk_mul_f32 v[116:117], v[4:5], v[86:87]
	v_add_f32_dpp v10, v10, v10 row_ror:8 row_mask:0xf bank_mask:0xf bound_ctrl:1
	v_add_f32_dpp v11, v11, v11 row_ror:8 row_mask:0xf bank_mask:0xf bound_ctrl:1
	ds_read_b128 v[32:35], v6 offset:28416
	v_pk_fma_f32 v[14:15], v[4:5], v[82:83], v[14:15] op_sel:[1,0,0] op_sel_hi:[1,1,1]
	v_add_f32_dpp v10, v10, v10 row_ror:4 row_mask:0xf bank_mask:0xf bound_ctrl:1
	ds_read_b128 v[36:39], v6 offset:28672
	v_add_f32_dpp v11, v11, v11 row_ror:4 row_mask:0xf bank_mask:0xf bound_ctrl:1
	v_pk_fma_f32 v[114:115], v[88:89], v[104:105], v[114:115] op_sel_hi:[1,0,1]
	v_add_f32_dpp v10, v10, v10 row_ror:2 row_mask:0xf bank_mask:0xf bound_ctrl:1
	ds_read_b128 v[40:43], v6 offset:28928
	v_add_f32_dpp v11, v11, v11 row_ror:2 row_mask:0xf bank_mask:0xf bound_ctrl:1
	v_pk_fma_f32 v[116:117], v[90:91], v[104:105], v[116:117] op_sel_hi:[1,0,1]
	ds_read_b128 v[48:51], v6 offset:29440
	v_add_f32_dpp v10, v10, v10 row_ror:1 row_mask:0xf bank_mask:0xf bound_ctrl:1
	v_add_f32_dpp v11, v11, v11 row_ror:1 row_mask:0xf bank_mask:0xf bound_ctrl:1
	s_waitcnt lgkmcnt(9)
	v_pk_fma_f32 v[114:115], v[96:97], v[104:105], v[114:115] op_sel:[0,1,0] op_sel_hi:[1,1,1]
	ds_read_b128 v[44:47], v6 offset:29184
	v_pk_fma_f32 v[116:117], v[98:99], v[104:105], v[116:117] op_sel:[0,1,0] op_sel_hi:[1,1,1]
	v_pk_fma_f32 v[114:115], v[92:93], v[10:11], v[114:115] op_sel_hi:[1,0,1] neg_lo:[1,0,0] neg_hi:[1,0,0]
	ds_read_b128 v[52:55], v6 offset:29696
	v_pk_fma_f32 v[116:117], v[94:95], v[10:11], v[116:117] op_sel_hi:[1,0,1] neg_lo:[1,0,0] neg_hi:[1,0,0]
	v_pk_fma_f32 v[2:3], v[100:101], v[10:11], v[114:115] op_sel:[0,1,0] op_sel_hi:[1,1,1] neg_lo:[1,0,0] neg_hi:[1,0,0]
	v_pk_fma_f32 v[4:5], v[102:103], v[10:11], v[116:117] op_sel:[0,1,0] op_sel_hi:[1,1,1] neg_lo:[1,0,0] neg_hi:[1,0,0]
	ds_write2st64_b32 v9, v14, v15 offset0:88 offset1:92
	s_waitcnt lgkmcnt(6)
	v_pk_mul_f32 v[10:11], v[2:3], v[20:21] op_sel_hi:[0,1]
	ds_read_b128 v[68:71], v6 offset:29952
	v_pk_fma_f32 v[14:15], v[2:3], v[24:25], v[58:59] op_sel_hi:[0,1,1]
	v_pk_fma_f32 v[10:11], v[2:3], v[22:23], v[10:11] op_sel:[1,0,0] op_sel_hi:[1,1,1]
	ds_read_b128 v[72:75], v6 offset:30208
	v_pk_fma_f32 v[14:15], v[2:3], v[26:27], v[14:15] op_sel:[1,0,0] op_sel_hi:[1,1,1]
	v_pk_fma_f32 v[10:11], v[4:5], v[28:29], v[10:11] op_sel_hi:[0,1,1]
	v_pk_fma_f32 v[14:15], v[4:5], v[32:33], v[14:15] op_sel_hi:[0,1,1]
	ds_read_b128 v[104:107], v7 offset:3328
	v_pk_fma_f32 v[10:11], v[4:5], v[30:31], v[10:11] op_sel:[1,0,0] op_sel_hi:[1,1,1]
	s_waitcnt lgkmcnt(7)
	v_pk_mul_f32 v[114:115], v[2:3], v[36:37]
	ds_read_b128 v[76:79], v6 offset:30464
	v_pk_mul_f32 v[116:117], v[4:5], v[38:39]
	v_add_f32_dpp v10, v10, v10 row_ror:8 row_mask:0xf bank_mask:0xf bound_ctrl:1
	v_add_f32_dpp v11, v11, v11 row_ror:8 row_mask:0xf bank_mask:0xf bound_ctrl:1
	ds_read_b128 v[80:83], v6 offset:30720
	v_pk_fma_f32 v[14:15], v[4:5], v[34:35], v[14:15] op_sel:[1,0,0] op_sel_hi:[1,1,1]
	v_add_f32_dpp v10, v10, v10 row_ror:4 row_mask:0xf bank_mask:0xf bound_ctrl:1
	ds_read_b128 v[84:87], v6 offset:30976
	v_add_f32_dpp v11, v11, v11 row_ror:4 row_mask:0xf bank_mask:0xf bound_ctrl:1
	v_pk_fma_f32 v[114:115], v[40:41], v[56:57], v[114:115] op_sel_hi:[1,0,1]
	v_add_f32_dpp v10, v10, v10 row_ror:2 row_mask:0xf bank_mask:0xf bound_ctrl:1
	ds_read_b128 v[88:91], v6 offset:31232
	v_add_f32_dpp v11, v11, v11 row_ror:2 row_mask:0xf bank_mask:0xf bound_ctrl:1
	v_pk_fma_f32 v[116:117], v[42:43], v[56:57], v[116:117] op_sel_hi:[1,0,1]
	ds_read_b128 v[96:99], v6 offset:31744
	v_add_f32_dpp v10, v10, v10 row_ror:1 row_mask:0xf bank_mask:0xf bound_ctrl:1
	v_add_f32_dpp v11, v11, v11 row_ror:1 row_mask:0xf bank_mask:0xf bound_ctrl:1
	s_waitcnt lgkmcnt(9)
	v_pk_fma_f32 v[114:115], v[48:49], v[56:57], v[114:115] op_sel:[0,1,0] op_sel_hi:[1,1,1]
	ds_read_b128 v[92:95], v6 offset:31488
	v_pk_fma_f32 v[116:117], v[50:51], v[56:57], v[116:117] op_sel:[0,1,0] op_sel_hi:[1,1,1]
	v_pk_fma_f32 v[114:115], v[44:45], v[10:11], v[114:115] op_sel_hi:[1,0,1] neg_lo:[1,0,0] neg_hi:[1,0,0]
	ds_read_b128 v[100:103], v6 offset:32000
	v_pk_fma_f32 v[116:117], v[46:47], v[10:11], v[116:117] op_sel_hi:[1,0,1] neg_lo:[1,0,0] neg_hi:[1,0,0]
	v_pk_fma_f32 v[2:3], v[52:53], v[10:11], v[114:115] op_sel:[0,1,0] op_sel_hi:[1,1,1] neg_lo:[1,0,0] neg_hi:[1,0,0]
	v_pk_fma_f32 v[4:5], v[54:55], v[10:11], v[116:117] op_sel:[0,1,0] op_sel_hi:[1,1,1] neg_lo:[1,0,0] neg_hi:[1,0,0]
	ds_write2st64_b32 v9, v14, v15 offset0:96 offset1:100
	s_waitcnt lgkmcnt(6)
	v_pk_mul_f32 v[10:11], v[2:3], v[68:69] op_sel_hi:[0,1]
	ds_read_b128 v[20:23], v6 offset:32256
	v_pk_fma_f32 v[14:15], v[2:3], v[72:73], v[106:107] op_sel_hi:[0,1,1]
	v_pk_fma_f32 v[10:11], v[2:3], v[70:71], v[10:11] op_sel:[1,0,0] op_sel_hi:[1,1,1]
	ds_read_b128 v[24:27], v6 offset:32512
	v_pk_fma_f32 v[14:15], v[2:3], v[74:75], v[14:15] op_sel:[1,0,0] op_sel_hi:[1,1,1]
	v_pk_fma_f32 v[10:11], v[4:5], v[76:77], v[10:11] op_sel_hi:[0,1,1]
	v_pk_fma_f32 v[14:15], v[4:5], v[80:81], v[14:15] op_sel_hi:[0,1,1]
	ds_read_b128 v[56:59], v7 offset:3584
	v_pk_fma_f32 v[10:11], v[4:5], v[78:79], v[10:11] op_sel:[1,0,0] op_sel_hi:[1,1,1]
	s_waitcnt lgkmcnt(7)
	v_pk_mul_f32 v[114:115], v[2:3], v[84:85]
	ds_read_b128 v[28:31], v6 offset:32768
	v_pk_mul_f32 v[116:117], v[4:5], v[86:87]
	v_add_f32_dpp v10, v10, v10 row_ror:8 row_mask:0xf bank_mask:0xf bound_ctrl:1
	v_add_f32_dpp v11, v11, v11 row_ror:8 row_mask:0xf bank_mask:0xf bound_ctrl:1
	ds_read_b128 v[32:35], v6 offset:33024
	v_pk_fma_f32 v[14:15], v[4:5], v[82:83], v[14:15] op_sel:[1,0,0] op_sel_hi:[1,1,1]
	v_add_f32_dpp v10, v10, v10 row_ror:4 row_mask:0xf bank_mask:0xf bound_ctrl:1
	ds_read_b128 v[36:39], v6 offset:33280
	v_add_f32_dpp v11, v11, v11 row_ror:4 row_mask:0xf bank_mask:0xf bound_ctrl:1
	v_pk_fma_f32 v[114:115], v[88:89], v[104:105], v[114:115] op_sel_hi:[1,0,1]
	v_add_f32_dpp v10, v10, v10 row_ror:2 row_mask:0xf bank_mask:0xf bound_ctrl:1
	ds_read_b128 v[40:43], v6 offset:33536
	v_add_f32_dpp v11, v11, v11 row_ror:2 row_mask:0xf bank_mask:0xf bound_ctrl:1
	v_pk_fma_f32 v[116:117], v[90:91], v[104:105], v[116:117] op_sel_hi:[1,0,1]
	ds_read_b128 v[48:51], v6 offset:34048
	v_add_f32_dpp v10, v10, v10 row_ror:1 row_mask:0xf bank_mask:0xf bound_ctrl:1
	v_add_f32_dpp v11, v11, v11 row_ror:1 row_mask:0xf bank_mask:0xf bound_ctrl:1
	s_waitcnt lgkmcnt(9)
	v_pk_fma_f32 v[114:115], v[96:97], v[104:105], v[114:115] op_sel:[0,1,0] op_sel_hi:[1,1,1]
	ds_read_b128 v[44:47], v6 offset:33792
	v_pk_fma_f32 v[116:117], v[98:99], v[104:105], v[116:117] op_sel:[0,1,0] op_sel_hi:[1,1,1]
	v_pk_fma_f32 v[114:115], v[92:93], v[10:11], v[114:115] op_sel_hi:[1,0,1] neg_lo:[1,0,0] neg_hi:[1,0,0]
	ds_read_b128 v[52:55], v6 offset:34304
	v_pk_fma_f32 v[116:117], v[94:95], v[10:11], v[116:117] op_sel_hi:[1,0,1] neg_lo:[1,0,0] neg_hi:[1,0,0]
	v_pk_fma_f32 v[2:3], v[100:101], v[10:11], v[114:115] op_sel:[0,1,0] op_sel_hi:[1,1,1] neg_lo:[1,0,0] neg_hi:[1,0,0]
	v_pk_fma_f32 v[4:5], v[102:103], v[10:11], v[116:117] op_sel:[0,1,0] op_sel_hi:[1,1,1] neg_lo:[1,0,0] neg_hi:[1,0,0]
	ds_write2st64_b32 v9, v14, v15 offset0:104 offset1:108
	s_waitcnt lgkmcnt(6)
	v_pk_mul_f32 v[10:11], v[2:3], v[20:21] op_sel_hi:[0,1]
	ds_read_b128 v[68:71], v6 offset:34560
	v_pk_fma_f32 v[14:15], v[2:3], v[24:25], v[58:59] op_sel_hi:[0,1,1]
	v_pk_fma_f32 v[10:11], v[2:3], v[22:23], v[10:11] op_sel:[1,0,0] op_sel_hi:[1,1,1]
	ds_read_b128 v[72:75], v6 offset:34816
	v_pk_fma_f32 v[14:15], v[2:3], v[26:27], v[14:15] op_sel:[1,0,0] op_sel_hi:[1,1,1]
	v_pk_fma_f32 v[10:11], v[4:5], v[28:29], v[10:11] op_sel_hi:[0,1,1]
	v_pk_fma_f32 v[14:15], v[4:5], v[32:33], v[14:15] op_sel_hi:[0,1,1]
	ds_read_b128 v[104:107], v7 offset:3840
	v_pk_fma_f32 v[10:11], v[4:5], v[30:31], v[10:11] op_sel:[1,0,0] op_sel_hi:[1,1,1]
	s_waitcnt lgkmcnt(7)
	v_pk_mul_f32 v[114:115], v[2:3], v[36:37]
	ds_read_b128 v[76:79], v6 offset:35072
	v_pk_mul_f32 v[116:117], v[4:5], v[38:39]
	v_add_f32_dpp v10, v10, v10 row_ror:8 row_mask:0xf bank_mask:0xf bound_ctrl:1
	v_add_f32_dpp v11, v11, v11 row_ror:8 row_mask:0xf bank_mask:0xf bound_ctrl:1
	ds_read_b128 v[80:83], v6 offset:35328
	v_pk_fma_f32 v[14:15], v[4:5], v[34:35], v[14:15] op_sel:[1,0,0] op_sel_hi:[1,1,1]
	v_add_f32_dpp v10, v10, v10 row_ror:4 row_mask:0xf bank_mask:0xf bound_ctrl:1
	ds_read_b128 v[84:87], v6 offset:35584
	v_add_f32_dpp v11, v11, v11 row_ror:4 row_mask:0xf bank_mask:0xf bound_ctrl:1
	v_pk_fma_f32 v[114:115], v[40:41], v[56:57], v[114:115] op_sel_hi:[1,0,1]
	v_add_f32_dpp v10, v10, v10 row_ror:2 row_mask:0xf bank_mask:0xf bound_ctrl:1
	ds_read_b128 v[88:91], v6 offset:35840
	v_add_f32_dpp v11, v11, v11 row_ror:2 row_mask:0xf bank_mask:0xf bound_ctrl:1
	v_pk_fma_f32 v[116:117], v[42:43], v[56:57], v[116:117] op_sel_hi:[1,0,1]
	ds_read_b128 v[96:99], v6 offset:36352
	v_add_f32_dpp v10, v10, v10 row_ror:1 row_mask:0xf bank_mask:0xf bound_ctrl:1
	v_add_f32_dpp v11, v11, v11 row_ror:1 row_mask:0xf bank_mask:0xf bound_ctrl:1
	s_waitcnt lgkmcnt(9)
	v_pk_fma_f32 v[114:115], v[48:49], v[56:57], v[114:115] op_sel:[0,1,0] op_sel_hi:[1,1,1]
	ds_read_b128 v[92:95], v6 offset:36096
	v_pk_fma_f32 v[116:117], v[50:51], v[56:57], v[116:117] op_sel:[0,1,0] op_sel_hi:[1,1,1]
	v_pk_fma_f32 v[114:115], v[44:45], v[10:11], v[114:115] op_sel_hi:[1,0,1] neg_lo:[1,0,0] neg_hi:[1,0,0]
	ds_read_b128 v[100:103], v6 offset:36608
	v_pk_fma_f32 v[116:117], v[46:47], v[10:11], v[116:117] op_sel_hi:[1,0,1] neg_lo:[1,0,0] neg_hi:[1,0,0]
	v_pk_fma_f32 v[2:3], v[52:53], v[10:11], v[114:115] op_sel:[0,1,0] op_sel_hi:[1,1,1] neg_lo:[1,0,0] neg_hi:[1,0,0]
	v_pk_fma_f32 v[4:5], v[54:55], v[10:11], v[116:117] op_sel:[0,1,0] op_sel_hi:[1,1,1] neg_lo:[1,0,0] neg_hi:[1,0,0]
	ds_write2st64_b32 v9, v14, v15 offset0:112 offset1:116
	s_waitcnt lgkmcnt(6)
	v_pk_mul_f32 v[10:11], v[2:3], v[68:69] op_sel_hi:[0,1]
	v_pk_fma_f32 v[14:15], v[2:3], v[72:73], v[106:107] op_sel_hi:[0,1,1]
	v_pk_fma_f32 v[10:11], v[2:3], v[70:71], v[10:11] op_sel:[1,0,0] op_sel_hi:[1,1,1]
	v_pk_fma_f32 v[14:15], v[2:3], v[74:75], v[14:15] op_sel:[1,0,0] op_sel_hi:[1,1,1]
	v_pk_fma_f32 v[10:11], v[4:5], v[76:77], v[10:11] op_sel_hi:[0,1,1]
	v_pk_fma_f32 v[14:15], v[4:5], v[80:81], v[14:15] op_sel_hi:[0,1,1]
	v_pk_fma_f32 v[10:11], v[4:5], v[78:79], v[10:11] op_sel:[1,0,0] op_sel_hi:[1,1,1]
	s_waitcnt lgkmcnt(4)
	v_pk_mul_f32 v[114:115], v[2:3], v[84:85]
	v_pk_mul_f32 v[116:117], v[4:5], v[86:87]
	v_add_f32_dpp v10, v10, v10 row_ror:8 row_mask:0xf bank_mask:0xf bound_ctrl:1
	v_add_f32_dpp v11, v11, v11 row_ror:8 row_mask:0xf bank_mask:0xf bound_ctrl:1
	v_pk_fma_f32 v[14:15], v[4:5], v[82:83], v[14:15] op_sel:[1,0,0] op_sel_hi:[1,1,1]
	v_add_f32_dpp v10, v10, v10 row_ror:4 row_mask:0xf bank_mask:0xf bound_ctrl:1
	v_add_f32_dpp v11, v11, v11 row_ror:4 row_mask:0xf bank_mask:0xf bound_ctrl:1
	v_pk_fma_f32 v[114:115], v[88:89], v[104:105], v[114:115] op_sel_hi:[1,0,1]
	v_add_f32_dpp v10, v10, v10 row_ror:2 row_mask:0xf bank_mask:0xf bound_ctrl:1
	v_add_f32_dpp v11, v11, v11 row_ror:2 row_mask:0xf bank_mask:0xf bound_ctrl:1
	v_pk_fma_f32 v[116:117], v[90:91], v[104:105], v[116:117] op_sel_hi:[1,0,1]
	v_add_f32_dpp v10, v10, v10 row_ror:1 row_mask:0xf bank_mask:0xf bound_ctrl:1
	v_add_f32_dpp v11, v11, v11 row_ror:1 row_mask:0xf bank_mask:0xf bound_ctrl:1
	s_waitcnt lgkmcnt(1)
	v_pk_fma_f32 v[114:115], v[96:97], v[104:105], v[114:115] op_sel:[0,1,0] op_sel_hi:[1,1,1]
	v_pk_fma_f32 v[116:117], v[98:99], v[104:105], v[116:117] op_sel:[0,1,0] op_sel_hi:[1,1,1]
	v_pk_fma_f32 v[114:115], v[92:93], v[10:11], v[114:115] op_sel_hi:[1,0,1] neg_lo:[1,0,0] neg_hi:[1,0,0]
	v_pk_fma_f32 v[116:117], v[94:95], v[10:11], v[116:117] op_sel_hi:[1,0,1] neg_lo:[1,0,0] neg_hi:[1,0,0]
	v_pk_fma_f32 v[2:3], v[100:101], v[10:11], v[114:115] op_sel:[0,1,0] op_sel_hi:[1,1,1] neg_lo:[1,0,0] neg_hi:[1,0,0]
	v_pk_fma_f32 v[4:5], v[102:103], v[10:11], v[116:117] op_sel:[0,1,0] op_sel_hi:[1,1,1] neg_lo:[1,0,0] neg_hi:[1,0,0]
	ds_write2st64_b32 v9, v14, v15 offset0:120 offset1:124
	v_add_u32_e32 v6, s1, v6
	v_add_u32_e32 v7, vcc_lo, v7
	v_add_u32_e32 v9, s1, v9
	s_sub_i32 s1, 0, s1
	s_sub_i32 vcc_lo, 0, vcc_lo
	s_add_i32 s0, s0, 1
	s_cmpk_eq_i32 s0, 0x200
	s_waitcnt lgkmcnt(0)
	s_barrier
	s_cbranch_scc0 .LBB0_652
	s_mov_b64 s[0:1], 0
.LBB0_654:
	s_and_b64 vcc, exec, s[0:1]
	s_cbranch_vccz .LBB0_676
	v_bfe_u32 v214, v153, 4, 4
	v_and_b32_e32 v215, 15, v153
	v_mul_u32_u24_e32 v216, 48, v214
	v_add_u32_e32 v217, 0x11b00, v216
	v_mul_u32_u24_e32 v218, 0x900, v214
	v_lshl_add_u32 v218, v215, 4, v218
	v_add_u32_e32 v219, 0x11b00, v218
	v_lshlrev_b32_e32 v220, 7, v214
	v_lshl_add_u32 v220, v215, 2, v220
	v_add_u32_e32 v220, 0x9300, v220
	v_add_u32_e32 v221, 0x11b00, v220
	v_lshlrev_b32_e32 v222, 8, v214
	v_lshl_add_u32 v222, v215, 4, v222
	v_add_u32_e32 v222, 0x23600, v222
	v_add_u32_e32 v223, 0x1000, v222
	s_lshl_b32 s0, s2, 8
	s_and_b32 s4, s0, 0x4000
	s_add_u32 s12, s70, 0x4000000
	s_addc_u32 s13, s71, 0
	s_add_u32 s14, s70, 0x8000000
	s_addc_u32 s15, s71, 0
	s_add_u32 s20, s70, 0xc000000
	s_addc_u32 s21, s71, 0
	s_add_u32 s16, s78, 0x30000000
	s_addc_u32 s17, s79, 0
	s_add_u32 s18, s78, 0x34000000
	s_addc_u32 s19, s79, 0
	s_and_b32 s0, s2, 0x60
	s_lshl_b32 s24, s2, 2
	s_bfe_u32 s6, s2, 0x20003
	v_add_u32_e32 v20, 0xffffff00, v153
	s_and_b32 s1, s24, 28
	s_or_b32 s0, s6, s0
	v_ashrrev_i32_e32 v1, 4, v20
	s_or_b32 s25, s0, s1
	v_lshlrev_b32_e32 v26, 1, v1
	s_mov_b32 s5, 0
	s_lshl_b32 s0, s25, 4
	v_and_b32_e32 v23, 15, v153
	v_ashrrev_i32_e32 v27, 31, v26
	s_and_b32 s1, s0, 0x3c0
	v_lshlrev_b32_e32 v22, 2, v23
	v_lshl_add_u64 v[2:3], v[26:27], 0, s[4:5]
	v_or_b32_e32 v55, s1, v22
	v_lshlrev_b64 v[28:29], 10, v[2:3]
	v_or_b32_e32 v2, v28, v55
	v_mov_b32_e32 v3, v29
	v_lshlrev_b64 v[6:7], 1, v[2:3]
	v_lshl_add_u64 v[4:5], s[16:17], 0, v[6:7]
	v_lshl_add_u64 v[2:3], s[70:71], 0, v[6:7]
	global_load_dwordx2 v[8:9], v[4:5], off
	v_lshl_add_u64 v[4:5], s[12:13], 0, v[6:7]
	global_load_dwordx2 v[10:11], v[4:5], off
	v_lshl_add_u64 v[4:5], s[14:15], 0, v[6:7]
	global_load_dwordx2 v[12:13], v[2:3], off
	global_load_dwordx2 v[24:25], v[4:5], off
	global_load_dwordx2 v[14:15], v[2:3], off offset:2048
	v_lshl_add_u64 v[2:3], s[18:19], 0, v[6:7]
	v_or_b32_e32 v6, 0x800, v6
	v_lshl_add_u64 v[4:5], s[12:13], 0, v[6:7]
	global_load_dwordx2 v[16:17], v[4:5], off
	v_lshl_add_u64 v[4:5], s[16:17], 0, v[6:7]
	global_load_dwordx2 v[18:19], v[4:5], off
	global_load_dwordx2 v[38:39], v[2:3], off
	v_ashrrev_i32_e32 v4, 3, v20
	v_ashrrev_i32_e32 v5, 31, v4
	v_lshl_add_u64 v[30:31], s[4:5], 0, v[4:5]
	v_lshlrev_b64 v[32:33], 11, v[30:31]
	v_lshlrev_b32_e32 v2, 1, v153
	s_mov_b32 s7, s5
	v_lshl_add_u64 v[20:21], s[20:21], 0, v[32:33]
	s_and_b32 s0, s0, 48
	s_lshl_b32 s6, s1, 1
	s_mov_b32 s9, s5
	v_and_b32_e32 v58, 14, v2
	s_lshl_b32 s8, s0, 1
	v_lshl_add_u64 v[20:21], v[20:21], 0, s[6:7]
	v_mov_b32_e32 v3, 0
	v_lshlrev_b32_e32 v2, 1, v58
	v_lshl_add_u64 v[20:21], v[20:21], 0, s[8:9]
	v_lshl_add_u64 v[20:21], v[20:21], 0, v[2:3]
	v_lshl_add_u64 v[34:35], s[14:15], 0, v[6:7]
	v_lshl_add_u64 v[6:7], s[18:19], 0, v[6:7]
	global_load_dword v3, v[20:21], off
	global_load_dwordx2 v[40:41], v[34:35], off
	global_load_dwordx2 v[42:43], v[6:7], off
	v_lshl_add_u32 v59, v23, 4, 0
	s_movk_i32 s0, 0x900
	v_mad_i32_i24 v54, v1, s0, v59
	v_cmp_eq_u32_e64 s[0:1], 0, v23
	v_cmp_ne_u32_e32 vcc, 0, v23
	v_mul_i32_i24_e32 v23, 48, v1
	s_waitcnt vmcnt(0)
	v_cvt_f32_f16_e32 v6, v8
	v_cvt_f32_f16_sdwa v7, v8 dst_sel:DWORD dst_unused:UNUSED_PAD src0_sel:WORD_1
	v_cvt_f32_f16_e32 v20, v10
	v_cvt_f32_f16_sdwa v21, v10 dst_sel:DWORD dst_unused:UNUSED_PAD src0_sel:WORD_1
	v_cvt_f32_f16_e32 v44, v12
	v_cvt_f32_f16_sdwa v45, v12 dst_sel:DWORD dst_unused:UNUSED_PAD src0_sel:WORD_1
	v_cvt_f32_f16_e32 v46, v14
	v_cvt_f32_f16_sdwa v47, v14 dst_sel:DWORD dst_unused:UNUSED_PAD src0_sel:WORD_1
	v_cvt_f32_f16_e32 v10, v11
	v_cvt_f32_f16_sdwa v11, v11 dst_sel:DWORD dst_unused:UNUSED_PAD src0_sel:WORD_1
	v_cvt_f32_f16_e32 v48, v13
	v_cvt_f32_f16_sdwa v49, v13 dst_sel:DWORD dst_unused:UNUSED_PAD src0_sel:WORD_1
	v_cvt_f32_f16_e32 v50, v15
	v_cvt_f32_f16_sdwa v51, v15 dst_sel:DWORD dst_unused:UNUSED_PAD src0_sel:WORD_1
	v_cvt_f32_f16_e32 v12, v16
	v_cvt_f32_f16_sdwa v13, v16 dst_sel:DWORD dst_unused:UNUSED_PAD src0_sel:WORD_1
	v_cvt_f32_f16_e32 v14, v17
	v_cvt_f32_f16_sdwa v15, v17 dst_sel:DWORD dst_unused:UNUSED_PAD src0_sel:WORD_1
	v_cvt_f32_f16_e32 v52, v18
	v_cvt_f32_f16_sdwa v53, v18 dst_sel:DWORD dst_unused:UNUSED_PAD src0_sel:WORD_1
	v_cvt_f32_f16_e32 v56, v19
	v_cvt_f32_f16_sdwa v57, v19 dst_sel:DWORD dst_unused:UNUSED_PAD src0_sel:WORD_1
	v_cvt_f32_f16_e32 v8, v9
	v_cvt_f32_f16_sdwa v9, v9 dst_sel:DWORD dst_unused:UNUSED_PAD src0_sel:WORD_1
	v_pk_add_f32 v[20:21], v[20:21], 1.0 op_sel_hi:[1,0] neg_lo:[1,0] neg_hi:[1,0]
	v_pk_add_f32 v[60:61], v[10:11], 1.0 op_sel_hi:[1,0] neg_lo:[1,0] neg_hi:[1,0]
	v_pk_add_f32 v[62:63], v[12:13], 1.0 op_sel_hi:[1,0] neg_lo:[1,0] neg_hi:[1,0]
	v_pk_add_f32 v[64:65], v[14:15], 1.0 op_sel_hi:[1,0] neg_lo:[1,0] neg_hi:[1,0]
	v_pk_mul_f32 v[14:15], v[20:21], v[52:53]
	v_pk_mul_f32 v[16:17], v[60:61], v[56:57]
	v_pk_mul_f32 v[66:67], v[62:63], v[46:47]
	v_pk_mul_f32 v[68:69], v[64:65], v[50:51]
	v_pk_mul_f32 v[10:11], v[20:21], v[44:45]
	v_pk_mul_f32 v[12:13], v[60:61], v[48:49]
	v_pk_mul_f32 v[18:19], v[20:21], v[62:63]
	v_pk_mul_f32 v[34:35], v[20:21], v[66:67]
	v_pk_mul_f32 v[36:37], v[60:61], v[68:69]
	v_pk_mul_f32 v[20:21], v[60:61], v[64:65]
	v_mov_b32_e32 v120, v6
	v_mov_b32_e32 v121, v14
	v_mov_b32_e32 v122, v7
	v_mov_b32_e32 v123, v15
	v_mov_b32_e32 v124, v10
	v_mov_b32_e32 v125, v34
	v_mov_b32_e32 v126, v11
	v_mov_b32_e32 v127, v35
	v_mov_b32_e32 v128, v8
	v_mov_b32_e32 v129, v16
	v_mov_b32_e32 v130, v9
	v_mov_b32_e32 v131, v17
	v_mov_b32_e32 v132, v12
	v_mov_b32_e32 v133, v36
	v_mov_b32_e32 v134, v13
	v_mov_b32_e32 v135, v37
	ds_write_b128 v54, v[18:21] offset:1024
	v_cvt_f32_f16_e32 v14, v38
	v_cvt_f32_f16_sdwa v16, v38 dst_sel:DWORD dst_unused:UNUSED_PAD src0_sel:WORD_1
	v_cvt_f32_f16_e32 v15, v24
	v_cvt_f32_f16_sdwa v17, v24 dst_sel:DWORD dst_unused:UNUSED_PAD src0_sel:WORD_1
	v_cvt_f32_f16_e32 v21, v25
	v_cvt_f32_f16_sdwa v25, v25 dst_sel:DWORD dst_unused:UNUSED_PAD src0_sel:WORD_1
	v_cvt_f32_f16_e32 v20, v39
	v_cvt_f32_f16_sdwa v24, v39 dst_sel:DWORD dst_unused:UNUSED_PAD src0_sel:WORD_1
	v_mov_b32_e32 v8, v14
	v_mov_b32_e32 v9, v16
	v_mov_b32_e32 v6, v15
	v_mov_b32_e32 v7, v17
	v_pk_mul_f32 v[10:11], v[62:63], v[8:9]
	v_mov_b32_e32 v8, v21
	v_mov_b32_e32 v9, v25
	v_pk_mul_f32 v[6:7], v[62:63], v[6:7]
	v_pk_mul_f32 v[8:9], v[64:65], v[8:9]
	v_mov_b32_e32 v12, v20
	v_mov_b32_e32 v13, v24
	v_mov_b32_e32 v18, v53
	v_pk_mul_f32 v[12:13], v[64:65], v[12:13]
	v_mov_b32_e32 v182, v6
	v_mov_b32_e32 v183, v7
	v_mov_b32_e32 v184, v8
	v_mov_b32_e32 v185, v9
	ds_write_b128 v54, v[10:13] offset:1536
	v_pk_fma_f32 v[6:7], v[52:53], v[14:15], 0 op_sel_hi:[0,1,0]
	v_pk_fma_f32 v[6:7], v[18:19], v[16:17], v[6:7] op_sel_hi:[0,1,1]
	v_mov_b32_e32 v10, v45
	v_pk_fma_f32 v[18:19], v[44:45], v[14:15], 0 op_sel_hi:[0,1,0]
	v_pk_fma_f32 v[14:15], v[66:67], v[14:15], 0 op_sel_hi:[0,1,0]
	v_pk_fma_f32 v[10:11], v[10:11], v[16:17], v[18:19] op_sel_hi:[0,1,1]
	v_pk_fma_f32 v[14:15], v[66:67], v[16:17], v[14:15] op_sel:[1,0,0]
	v_mov_b32_e32 v34, v57
	v_pk_fma_f32 v[6:7], v[56:57], v[20:21], v[6:7] op_sel_hi:[0,1,1]
	v_mov_b32_e32 v12, v49
	v_pk_fma_f32 v[10:11], v[48:49], v[20:21], v[10:11] op_sel_hi:[0,1,1]
	v_pk_fma_f32 v[14:15], v[68:69], v[20:21], v[14:15] op_sel_hi:[0,1,1]
	v_pk_fma_f32 v[6:7], v[34:35], v[24:25], v[6:7] op_sel_hi:[0,1,1]
	v_pk_fma_f32 v[10:11], v[12:13], v[24:25], v[10:11] op_sel_hi:[0,1,1]
	v_pk_fma_f32 v[14:15], v[68:69], v[24:25], v[14:15] op_sel:[1,0,0]
	v_cvt_f32_f16_e32 v25, v40
	v_cvt_f32_f16_sdwa v35, v40 dst_sel:DWORD dst_unused:UNUSED_PAD src0_sel:WORD_1
	v_cvt_f32_f16_e32 v39, v41
	v_cvt_f32_f16_sdwa v41, v41 dst_sel:DWORD dst_unused:UNUSED_PAD src0_sel:WORD_1
	v_cvt_f32_f16_e32 v24, v42
	v_cvt_f32_f16_sdwa v34, v42 dst_sel:DWORD dst_unused:UNUSED_PAD src0_sel:WORD_1
	v_cvt_f32_f16_e32 v38, v43
	v_cvt_f32_f16_sdwa v40, v43 dst_sel:DWORD dst_unused:UNUSED_PAD src0_sel:WORD_1
	v_mov_b32_e32 v18, v25
	v_mov_b32_e32 v19, v35
	v_mov_b32_e32 v20, v39
	v_mov_b32_e32 v21, v41
	ds_write_b128 v54, v[18:21] offset:1792
	v_mov_b32_e32 v18, v24
	v_mov_b32_e32 v19, v34
	v_mov_b32_e32 v20, v38
	v_mov_b32_e32 v21, v40
	v_mov_b32_e32 v36, v47
	ds_write_b128 v54, v[18:21] offset:2048
	v_mov_b32_e32 v186, v18
	v_mov_b32_e32 v187, v19
	v_mov_b32_e32 v188, v20
	v_mov_b32_e32 v189, v21
	v_pk_fma_f32 v[18:19], v[46:47], v[24:25], 0 op_sel_hi:[0,1,0]
	v_pk_fma_f32 v[18:19], v[36:37], v[34:35], v[18:19] op_sel_hi:[0,1,1]
	v_mov_b32_e32 v42, v51
	v_pk_fma_f32 v[18:19], v[50:51], v[38:39], v[18:19] op_sel_hi:[0,1,1]
	v_pk_fma_f32 v[18:19], v[42:43], v[40:41], v[18:19] op_sel_hi:[0,1,1]
	v_mov_b32_dpp v8, v6 row_ror:8 row_mask:0xf bank_mask:0xf bound_ctrl:1
	v_mov_b32_dpp v9, v7 row_ror:8 row_mask:0xf bank_mask:0xf bound_ctrl:1
	v_mov_b32_dpp v12, v10 row_ror:8 row_mask:0xf bank_mask:0xf bound_ctrl:1
	v_mov_b32_dpp v13, v11 row_ror:8 row_mask:0xf bank_mask:0xf bound_ctrl:1
	v_mov_b32_dpp v16, v14 row_ror:8 row_mask:0xf bank_mask:0xf bound_ctrl:1
	v_mov_b32_dpp v17, v15 row_ror:8 row_mask:0xf bank_mask:0xf bound_ctrl:1
	v_mov_b32_dpp v20, v18 row_ror:8 row_mask:0xf bank_mask:0xf bound_ctrl:1
	v_mov_b32_dpp v21, v19 row_ror:8 row_mask:0xf bank_mask:0xf bound_ctrl:1
	v_pk_add_f32 v[6:7], v[6:7], v[8:9]
	v_pk_add_f32 v[10:11], v[10:11], v[12:13]
	v_pk_add_f32 v[14:15], v[14:15], v[16:17]
	v_pk_add_f32 v[18:19], v[18:19], v[20:21]
	v_mov_b32_dpp v8, v6 row_ror:4 row_mask:0xf bank_mask:0xf bound_ctrl:1
	v_mov_b32_dpp v9, v7 row_ror:4 row_mask:0xf bank_mask:0xf bound_ctrl:1
	v_mov_b32_dpp v12, v10 row_ror:4 row_mask:0xf bank_mask:0xf bound_ctrl:1
	v_mov_b32_dpp v13, v11 row_ror:4 row_mask:0xf bank_mask:0xf bound_ctrl:1
	v_mov_b32_dpp v16, v14 row_ror:4 row_mask:0xf bank_mask:0xf bound_ctrl:1
	v_mov_b32_dpp v17, v15 row_ror:4 row_mask:0xf bank_mask:0xf bound_ctrl:1
	v_mov_b32_dpp v20, v18 row_ror:4 row_mask:0xf bank_mask:0xf bound_ctrl:1
	v_mov_b32_dpp v21, v19 row_ror:4 row_mask:0xf bank_mask:0xf bound_ctrl:1
	v_pk_add_f32 v[6:7], v[6:7], v[8:9]
	v_pk_add_f32 v[10:11], v[10:11], v[12:13]
	v_pk_add_f32 v[14:15], v[14:15], v[16:17]
	v_pk_add_f32 v[18:19], v[18:19], v[20:21]
	v_mov_b32_dpp v8, v6 row_ror:2 row_mask:0xf bank_mask:0xf bound_ctrl:1
	v_mov_b32_dpp v9, v7 row_ror:2 row_mask:0xf bank_mask:0xf bound_ctrl:1
	v_mov_b32_dpp v12, v10 row_ror:2 row_mask:0xf bank_mask:0xf bound_ctrl:1
	v_mov_b32_dpp v13, v11 row_ror:2 row_mask:0xf bank_mask:0xf bound_ctrl:1
	v_mov_b32_dpp v16, v14 row_ror:2 row_mask:0xf bank_mask:0xf bound_ctrl:1
	v_mov_b32_dpp v17, v15 row_ror:2 row_mask:0xf bank_mask:0xf bound_ctrl:1
	v_mov_b32_dpp v20, v18 row_ror:2 row_mask:0xf bank_mask:0xf bound_ctrl:1
	v_mov_b32_dpp v21, v19 row_ror:2 row_mask:0xf bank_mask:0xf bound_ctrl:1
	v_pk_add_f32 v[6:7], v[6:7], v[8:9]
	v_pk_add_f32 v[10:11], v[10:11], v[12:13]
	v_pk_add_f32 v[14:15], v[14:15], v[16:17]
	v_pk_add_f32 v[18:19], v[18:19], v[20:21]
	v_mov_b32_dpp v8, v6 row_ror:1 row_mask:0xf bank_mask:0xf bound_ctrl:1
	v_mov_b32_dpp v9, v7 row_ror:1 row_mask:0xf bank_mask:0xf bound_ctrl:1
	v_mov_b32_dpp v12, v10 row_ror:1 row_mask:0xf bank_mask:0xf bound_ctrl:1
	v_mov_b32_dpp v13, v11 row_ror:1 row_mask:0xf bank_mask:0xf bound_ctrl:1
	v_mov_b32_dpp v16, v14 row_ror:1 row_mask:0xf bank_mask:0xf bound_ctrl:1
	v_mov_b32_dpp v17, v15 row_ror:1 row_mask:0xf bank_mask:0xf bound_ctrl:1
	v_mov_b32_dpp v20, v18 row_ror:1 row_mask:0xf bank_mask:0xf bound_ctrl:1
	v_mov_b32_dpp v21, v19 row_ror:1 row_mask:0xf bank_mask:0xf bound_ctrl:1
	s_and_saveexec_b64 s[10:11], vcc
	s_xor_b64 s[10:11], exec, s[10:11]
	v_mul_i32_i24_e32 v23, 48, v1
	s_or_saveexec_b64 s[10:11], s[10:11]
	v_mul_i32_i24_e32 v62, 0x900, v1
	s_xor_b64 exec, exec, s[10:11]
	s_cbranch_execz .LBB0_659
	v_pk_add_f32 v[6:7], v[6:7], v[8:9]
	v_pk_add_f32 v[8:9], v[10:11], v[12:13]
	s_mov_b32 s22, 0x3d800000
	v_pk_mul_f32 v[8:9], v[8:9], s[22:23] op_sel_hi:[1,0]
	v_mad_i32_i24 v1, v1, 48, 0
	ds_write_b128 v1, v[6:9] offset:36864
	v_pk_add_f32 v[6:7], v[14:15], v[16:17]
	v_pk_add_f32 v[8:9], v[18:19], v[20:21]
	v_pk_mul_f32 v[6:7], v[6:7], s[22:23] op_sel_hi:[1,0]
	v_pk_mul_f32 v[8:9], v[8:9], s[22:23] op_sel_hi:[1,0]
	ds_write_b128 v1, v[6:9] offset:36880
.LBB0_659:
	s_or_b64 exec, exec, s[10:11]
	s_or_b32 s22, s4, 32
	s_mov_b32 s23, s5
	v_lshl_add_u64 v[6:7], s[22:23], 0, v[26:27]
	v_lshlrev_b64 v[6:7], 11, v[6:7]
	v_lshlrev_b32_e32 v25, 1, v55
	v_or_b32_e32 v6, v6, v25
	v_lshl_add_u64 v[8:9], s[70:71], 0, v[6:7]
	v_lshl_add_u64 v[10:11], s[12:13], 0, v[6:7]
	v_lshl_add_u64 v[12:13], s[14:15], 0, v[6:7]
	v_lshl_add_u64 v[14:15], s[16:17], 0, v[6:7]
	v_lshl_add_u64 v[16:17], s[18:19], 0, v[6:7]
	v_or_b32_e32 v6, 0x800, v6
	global_load_dwordx2 v[10:11], v[10:11], off
	v_lshl_add_u64 v[18:19], s[12:13], 0, v[6:7]
	global_load_dwordx2 v[14:15], v[14:15], off
	s_nop 0
	global_load_dwordx2 v[18:19], v[18:19], off
	s_nop 0
	global_load_dwordx2 v[20:21], v[8:9], off
	global_load_dwordx2 v[56:57], v[12:13], off
	s_nop 0
	global_load_dwordx2 v[12:13], v[8:9], off offset:2048
	v_lshl_add_u64 v[8:9], s[16:17], 0, v[6:7]
	global_load_dwordx2 v[64:65], v[8:9], off
	global_load_dwordx2 v[68:69], v[16:17], off
	v_cvt_f32_f16_sdwa v9, v3 dst_sel:DWORD dst_unused:UNUSED_PAD src0_sel:WORD_1
	v_cvt_f32_f16_e32 v8, v3
	s_or_b32 s26, s4, 64
	s_mov_b32 s27, s5
	v_lshl_add_u64 v[34:35], s[22:23], 0, v[4:5]
	v_lshl_add_u64 v[36:37], s[26:27], 0, v[26:27]
	v_lshlrev_b32_e32 v1, 6, v4
	s_mov_b32 s11, 0
	v_lshlrev_b32_e32 v24, 2, v58
	v_lshl_add_u64 v[38:39], s[26:27], 0, v[4:5]
	v_lshlrev_b64 v[34:35], 11, v[34:35]
	v_lshlrev_b64 v[36:37], 11, v[36:37]
	v_add3_u32 v1, 0, v1, v24
	s_mov_b32 s7, s11
	v_lshlrev_b64 v[38:39], 11, v[38:39]
	v_lshl_add_u64 v[34:35], s[20:21], 0, v[34:35]
	v_or_b32_e32 v36, v36, v25
	v_lshl_add_u64 v[38:39], s[20:21], 0, v[38:39]
	ds_write_b64 v1, v[8:9] offset:37632
	ds_read_b128 v[198:201], v216 offset:36864
	ds_read_b128 v[202:205], v216 offset:36880
	ds_read2_b32 v[206:207], v220 offset1:16
	s_waitcnt lgkmcnt(0)
	v_mul_f32_e32 v210, 0x41800000, v200
	v_mul_f32_e32 v211, 0x41800000, v202
	v_mul_f32_e32 v212, 0x41800000, v204
	v_fma_f32 v213, -v204, v199, v203
	v_fma_f32 v121, -v198, v120, v121
	v_fma_f32 v124, -v210, v120, v124
	v_fma_f32 v125, -v211, v120, v125
	v_fma_f32 v123, -v198, v122, v123
	v_fma_f32 v126, -v210, v122, v126
	v_fma_f32 v127, -v211, v122, v127
	v_fma_f32 v129, -v198, v128, v129
	v_fma_f32 v132, -v210, v128, v132
	v_fma_f32 v133, -v211, v128, v133
	v_fma_f32 v131, -v198, v130, v131
	v_fma_f32 v134, -v210, v130, v134
	v_fma_f32 v135, -v211, v130, v135
	v_fma_f32 v182, -v199, v186, v182
	v_fma_f32 v183, -v199, v187, v183
	v_fma_f32 v184, -v199, v188, v184
	v_fma_f32 v185, -v199, v189, v185
	v_fma_f32 v125, -v212, v121, v125
	v_fma_f32 v127, -v212, v123, v127
	v_fma_f32 v133, -v212, v129, v133
	v_fma_f32 v135, -v212, v131, v135
	v_mul_f32_e32 v208, v206, v201
	v_mul_f32_e32 v209, v206, v213
	ds_write_b128 v218, v[120:123]
	v_fmac_f32_e32 v209, v207, v205
	ds_write_b128 v218, v[124:127] offset:256
	ds_write_b128 v218, v[128:131] offset:512
	ds_write_b128 v218, v[132:135] offset:768
	ds_write_b128 v218, v[182:185] offset:1280
	ds_write_b128 v222, v[206:209]
	v_lshl_add_u64 v[8:9], v[34:35], 0, s[6:7]
	v_lshl_add_u64 v[34:35], s[14:15], 0, v[36:37]
	v_lshl_add_u64 v[40:41], s[16:17], 0, v[36:37]
	v_lshl_add_u64 v[50:51], s[14:15], 0, v[6:7]
	v_lshl_add_u64 v[46:47], s[18:19], 0, v[36:37]
	v_lshl_add_u64 v[48:49], v[38:39], 0, s[6:7]
	v_lshl_add_u64 v[6:7], s[18:19], 0, v[6:7]
	global_load_dwordx2 v[38:39], v[34:35], off
	global_load_dwordx2 v[42:43], v[40:41], off
	s_nop 0
	global_load_dwordx2 v[40:41], v[46:47], off
	global_load_dwordx2 v[70:71], v[50:51], off
	global_load_dwordx2 v[72:73], v[6:7], off
	s_add_i32 s10, 0, 0x11b00
	s_mov_b32 s9, s11
	v_lshl_add_u64 v[16:17], s[70:71], 0, v[36:37]
	v_lshl_add_u64 v[44:45], s[12:13], 0, v[36:37]
	v_or_b32_e32 v36, 0x800, v36
	v_mov_b32_e32 v3, 0
	v_lshl_add_u32 v22, v22, 2, s10
	v_lshl_add_u64 v[8:9], v[8:9], 0, s[8:9]
	v_lshl_add_u64 v[34:35], s[12:13], 0, v[36:37]
	v_lshl_add_u64 v[46:47], s[14:15], 0, v[36:37]
	v_lshl_add_u64 v[66:67], s[16:17], 0, v[36:37]
	v_lshl_add_u64 v[36:37], s[18:19], 0, v[36:37]
	v_lshl_add_u64 v[48:49], v[48:49], 0, s[8:9]
	v_add_u32_e32 v76, v22, v62
	v_lshl_add_u64 v[6:7], v[8:9], 0, v[2:3]
	global_load_dwordx2 v[52:53], v[34:35], off
	s_nop 0
	global_load_dwordx2 v[34:35], v[46:47], off
	s_nop 0
	global_load_dwordx2 v[46:47], v[66:67], off
	s_nop 0
	global_load_dwordx2 v[36:37], v[36:37], off
	v_lshl_add_u64 v[8:9], v[48:49], 0, v[2:3]
	global_load_dwordx2 v[50:51], v[44:45], off
	global_load_dword v22, v[6:7], off
	global_load_dwordx2 v[48:49], v[16:17], off
	s_nop 0
	global_load_dwordx2 v[44:45], v[16:17], off offset:2048
	global_load_dword v61, v[8:9], off
	s_waitcnt lgkmcnt(0)
	s_barrier
	v_lshlrev_b32_e32 v60, 4, v4
	v_add_u32_e32 v77, 0, v23
	s_waitcnt vmcnt(19)
	v_cvt_f32_f16_e32 v16, v18
	v_cvt_f32_f16_sdwa v17, v18 dst_sel:DWORD dst_unused:UNUSED_PAD src0_sel:WORD_1
	v_cvt_f32_f16_e32 v8, v10
	v_cvt_f32_f16_sdwa v9, v10 dst_sel:DWORD dst_unused:UNUSED_PAD src0_sel:WORD_1
	v_cvt_f32_f16_e32 v10, v11
	v_pk_add_f32 v[78:79], v[16:17], 1.0 op_sel_hi:[1,0] neg_lo:[1,0] neg_hi:[1,0]
	v_cvt_f32_f16_e32 v16, v19
	v_cvt_f32_f16_sdwa v17, v19 dst_sel:DWORD dst_unused:UNUSED_PAD src0_sel:WORD_1
	v_cvt_f32_f16_sdwa v11, v11 dst_sel:DWORD dst_unused:UNUSED_PAD src0_sel:WORD_1
	s_waitcnt vmcnt(16)
	v_cvt_f32_f16_e32 v80, v12
	v_cvt_f32_f16_sdwa v81, v12 dst_sel:DWORD dst_unused:UNUSED_PAD src0_sel:WORD_1
	s_waitcnt vmcnt(15)
	v_cvt_f32_f16_e32 v82, v64
	v_cvt_f32_f16_sdwa v83, v64 dst_sel:DWORD dst_unused:UNUSED_PAD src0_sel:WORD_1
	v_cvt_f32_f16_e32 v92, v65
	v_cvt_f32_f16_sdwa v93, v65 dst_sel:DWORD dst_unused:UNUSED_PAD src0_sel:WORD_1
	v_cvt_f32_f16_e32 v94, v13
	v_cvt_f32_f16_sdwa v95, v13 dst_sel:DWORD dst_unused:UNUSED_PAD src0_sel:WORD_1
	v_cvt_f32_f16_e32 v6, v14
	v_cvt_f32_f16_sdwa v7, v14 dst_sel:DWORD dst_unused:UNUSED_PAD src0_sel:WORD_1
	v_cvt_f32_f16_e32 v74, v20
	v_pk_add_f32 v[66:67], v[8:9], 1.0 op_sel_hi:[1,0] neg_lo:[1,0] neg_hi:[1,0]
	v_cvt_f32_f16_sdwa v75, v20 dst_sel:DWORD dst_unused:UNUSED_PAD src0_sel:WORD_1
	v_cvt_f32_f16_e32 v8, v15
	v_cvt_f32_f16_sdwa v9, v15 dst_sel:DWORD dst_unused:UNUSED_PAD src0_sel:WORD_1
	v_cvt_f32_f16_e32 v90, v21
	v_cvt_f32_f16_sdwa v91, v21 dst_sel:DWORD dst_unused:UNUSED_PAD src0_sel:WORD_1
	v_pk_add_f32 v[86:87], v[16:17], 1.0 op_sel_hi:[1,0] neg_lo:[1,0] neg_hi:[1,0]
	v_pk_add_f32 v[88:89], v[10:11], 1.0 op_sel_hi:[1,0] neg_lo:[1,0] neg_hi:[1,0]
	v_pk_mul_f32 v[84:85], v[78:79], v[80:81]
	v_pk_mul_f32 v[14:15], v[66:67], v[82:83]
	v_pk_mul_f32 v[16:17], v[88:89], v[92:93]
	v_pk_mul_f32 v[96:97], v[86:87], v[94:95]
	v_pk_mul_f32 v[10:11], v[66:67], v[74:75]
	v_pk_mul_f32 v[12:13], v[88:89], v[90:91]
	v_pk_mul_f32 v[18:19], v[66:67], v[84:85]
	v_pk_mul_f32 v[20:21], v[88:89], v[96:97]
	v_pk_mul_f32 v[64:65], v[66:67], v[78:79]
	v_pk_mul_f32 v[66:67], v[88:89], v[86:87]
	v_mov_b32_e32 v120, v6
	v_mov_b32_e32 v121, v14
	v_mov_b32_e32 v122, v7
	v_mov_b32_e32 v123, v15
	v_mov_b32_e32 v124, v10
	v_mov_b32_e32 v125, v18
	v_mov_b32_e32 v126, v11
	v_mov_b32_e32 v127, v19
	v_mov_b32_e32 v128, v8
	v_mov_b32_e32 v129, v16
	v_mov_b32_e32 v130, v9
	v_mov_b32_e32 v131, v17
	v_mov_b32_e32 v132, v12
	v_mov_b32_e32 v133, v20
	v_mov_b32_e32 v134, v13
	v_mov_b32_e32 v135, v21
	ds_write_b128 v76, v[64:67] offset:1024
	s_waitcnt vmcnt(14)
	v_cvt_f32_f16_e32 v14, v68
	v_cvt_f32_f16_sdwa v16, v68 dst_sel:DWORD dst_unused:UNUSED_PAD src0_sel:WORD_1
	v_cvt_f32_f16_e32 v15, v56
	v_cvt_f32_f16_sdwa v17, v56 dst_sel:DWORD dst_unused:UNUSED_PAD src0_sel:WORD_1
	v_cvt_f32_f16_e32 v21, v57
	v_cvt_f32_f16_sdwa v57, v57 dst_sel:DWORD dst_unused:UNUSED_PAD src0_sel:WORD_1
	v_cvt_f32_f16_e32 v20, v69
	v_cvt_f32_f16_sdwa v56, v69 dst_sel:DWORD dst_unused:UNUSED_PAD src0_sel:WORD_1
	v_mov_b32_e32 v8, v14
	v_mov_b32_e32 v9, v16
	v_mov_b32_e32 v6, v15
	v_mov_b32_e32 v7, v17
	v_pk_mul_f32 v[10:11], v[78:79], v[8:9]
	v_mov_b32_e32 v8, v21
	v_mov_b32_e32 v9, v57
	v_pk_mul_f32 v[6:7], v[78:79], v[6:7]
	v_pk_mul_f32 v[8:9], v[86:87], v[8:9]
	v_mov_b32_e32 v12, v20
	v_mov_b32_e32 v13, v56
	v_mov_b32_e32 v18, v83
	v_pk_mul_f32 v[12:13], v[86:87], v[12:13]
	v_mov_b32_e32 v182, v6
	v_mov_b32_e32 v183, v7
	v_mov_b32_e32 v184, v8
	v_mov_b32_e32 v185, v9
	ds_write_b128 v76, v[10:13] offset:1536
	v_pk_fma_f32 v[6:7], v[82:83], v[14:15], 0 op_sel_hi:[0,1,0]
	v_pk_fma_f32 v[6:7], v[18:19], v[16:17], v[6:7] op_sel_hi:[0,1,1]
	v_mov_b32_e32 v10, v75
	v_pk_fma_f32 v[18:19], v[74:75], v[14:15], 0 op_sel_hi:[0,1,0]
	v_pk_fma_f32 v[14:15], v[84:85], v[14:15], 0 op_sel_hi:[0,1,0]
	v_pk_fma_f32 v[10:11], v[10:11], v[16:17], v[18:19] op_sel_hi:[0,1,1]
	v_pk_fma_f32 v[14:15], v[84:85], v[16:17], v[14:15] op_sel:[1,0,0]
	v_mov_b32_e32 v54, v93
	v_pk_fma_f32 v[6:7], v[92:93], v[20:21], v[6:7] op_sel_hi:[0,1,1]
	v_mov_b32_e32 v12, v91
	v_pk_fma_f32 v[10:11], v[90:91], v[20:21], v[10:11] op_sel_hi:[0,1,1]
	v_pk_fma_f32 v[14:15], v[96:97], v[20:21], v[14:15] op_sel_hi:[0,1,1]
	v_pk_fma_f32 v[6:7], v[54:55], v[56:57], v[6:7] op_sel_hi:[0,1,1]
	v_pk_fma_f32 v[10:11], v[12:13], v[56:57], v[10:11] op_sel_hi:[0,1,1]
	v_pk_fma_f32 v[14:15], v[96:97], v[56:57], v[14:15] op_sel:[1,0,0]
	s_waitcnt vmcnt(10)
	v_cvt_f32_f16_e32 v57, v70
	v_cvt_f32_f16_sdwa v65, v70 dst_sel:DWORD dst_unused:UNUSED_PAD src0_sel:WORD_1
	v_cvt_f32_f16_e32 v67, v71
	v_cvt_f32_f16_sdwa v69, v71 dst_sel:DWORD dst_unused:UNUSED_PAD src0_sel:WORD_1
	s_waitcnt vmcnt(9)
	v_cvt_f32_f16_e32 v56, v72
	v_cvt_f32_f16_sdwa v64, v72 dst_sel:DWORD dst_unused:UNUSED_PAD src0_sel:WORD_1
	v_cvt_f32_f16_e32 v66, v73
	v_cvt_f32_f16_sdwa v68, v73 dst_sel:DWORD dst_unused:UNUSED_PAD src0_sel:WORD_1
	v_mov_b32_e32 v18, v57
	v_mov_b32_e32 v19, v65
	v_mov_b32_e32 v20, v67
	v_mov_b32_e32 v21, v69
	ds_write_b128 v76, v[18:21] offset:1792
	v_mov_b32_e32 v18, v56
	v_mov_b32_e32 v19, v64
	v_mov_b32_e32 v20, v66
	v_mov_b32_e32 v21, v68
	v_mov_b32_e32 v54, v81
	ds_write_b128 v76, v[18:21] offset:2048
	v_mov_b32_e32 v186, v18
	v_mov_b32_e32 v187, v19
	v_mov_b32_e32 v188, v20
	v_mov_b32_e32 v189, v21
	v_pk_fma_f32 v[18:19], v[80:81], v[56:57], 0 op_sel_hi:[0,1,0]
	v_pk_fma_f32 v[18:19], v[54:55], v[64:65], v[18:19] op_sel_hi:[0,1,1]
	v_mov_b32_e32 v70, v95
	v_pk_fma_f32 v[18:19], v[94:95], v[66:67], v[18:19] op_sel_hi:[0,1,1]
	v_pk_fma_f32 v[18:19], v[70:71], v[68:69], v[18:19] op_sel_hi:[0,1,1]
	v_mov_b32_dpp v8, v6 row_ror:8 row_mask:0xf bank_mask:0xf bound_ctrl:1
	v_mov_b32_dpp v9, v7 row_ror:8 row_mask:0xf bank_mask:0xf bound_ctrl:1
	v_mov_b32_dpp v12, v10 row_ror:8 row_mask:0xf bank_mask:0xf bound_ctrl:1
	v_mov_b32_dpp v13, v11 row_ror:8 row_mask:0xf bank_mask:0xf bound_ctrl:1
	v_mov_b32_dpp v16, v14 row_ror:8 row_mask:0xf bank_mask:0xf bound_ctrl:1
	v_mov_b32_dpp v17, v15 row_ror:8 row_mask:0xf bank_mask:0xf bound_ctrl:1
	v_mov_b32_dpp v20, v18 row_ror:8 row_mask:0xf bank_mask:0xf bound_ctrl:1
	v_mov_b32_dpp v21, v19 row_ror:8 row_mask:0xf bank_mask:0xf bound_ctrl:1
	v_pk_add_f32 v[6:7], v[6:7], v[8:9]
	v_pk_add_f32 v[10:11], v[10:11], v[12:13]
	v_pk_add_f32 v[14:15], v[14:15], v[16:17]
	v_pk_add_f32 v[18:19], v[18:19], v[20:21]
	v_mov_b32_dpp v8, v6 row_ror:4 row_mask:0xf bank_mask:0xf bound_ctrl:1
	v_mov_b32_dpp v9, v7 row_ror:4 row_mask:0xf bank_mask:0xf bound_ctrl:1
	v_mov_b32_dpp v12, v10 row_ror:4 row_mask:0xf bank_mask:0xf bound_ctrl:1
	v_mov_b32_dpp v13, v11 row_ror:4 row_mask:0xf bank_mask:0xf bound_ctrl:1
	v_mov_b32_dpp v16, v14 row_ror:4 row_mask:0xf bank_mask:0xf bound_ctrl:1
	v_mov_b32_dpp v17, v15 row_ror:4 row_mask:0xf bank_mask:0xf bound_ctrl:1
	v_mov_b32_dpp v20, v18 row_ror:4 row_mask:0xf bank_mask:0xf bound_ctrl:1
	v_mov_b32_dpp v21, v19 row_ror:4 row_mask:0xf bank_mask:0xf bound_ctrl:1
	v_pk_add_f32 v[6:7], v[6:7], v[8:9]
	v_pk_add_f32 v[10:11], v[10:11], v[12:13]
	v_pk_add_f32 v[14:15], v[14:15], v[16:17]
	v_pk_add_f32 v[18:19], v[18:19], v[20:21]
	v_mov_b32_dpp v8, v6 row_ror:2 row_mask:0xf bank_mask:0xf bound_ctrl:1
	v_mov_b32_dpp v9, v7 row_ror:2 row_mask:0xf bank_mask:0xf bound_ctrl:1
	v_mov_b32_dpp v12, v10 row_ror:2 row_mask:0xf bank_mask:0xf bound_ctrl:1
	v_mov_b32_dpp v13, v11 row_ror:2 row_mask:0xf bank_mask:0xf bound_ctrl:1
	v_mov_b32_dpp v16, v14 row_ror:2 row_mask:0xf bank_mask:0xf bound_ctrl:1
	v_mov_b32_dpp v17, v15 row_ror:2 row_mask:0xf bank_mask:0xf bound_ctrl:1
	v_mov_b32_dpp v20, v18 row_ror:2 row_mask:0xf bank_mask:0xf bound_ctrl:1
	v_mov_b32_dpp v21, v19 row_ror:2 row_mask:0xf bank_mask:0xf bound_ctrl:1
	v_pk_add_f32 v[6:7], v[6:7], v[8:9]
	v_pk_add_f32 v[10:11], v[10:11], v[12:13]
	v_pk_add_f32 v[14:15], v[14:15], v[16:17]
	v_pk_add_f32 v[18:19], v[18:19], v[20:21]
	v_mov_b32_dpp v8, v6 row_ror:1 row_mask:0xf bank_mask:0xf bound_ctrl:1
	v_mov_b32_dpp v9, v7 row_ror:1 row_mask:0xf bank_mask:0xf bound_ctrl:1
	v_mov_b32_dpp v12, v10 row_ror:1 row_mask:0xf bank_mask:0xf bound_ctrl:1
	v_mov_b32_dpp v13, v11 row_ror:1 row_mask:0xf bank_mask:0xf bound_ctrl:1
	v_mov_b32_dpp v16, v14 row_ror:1 row_mask:0xf bank_mask:0xf bound_ctrl:1
	v_mov_b32_dpp v17, v15 row_ror:1 row_mask:0xf bank_mask:0xf bound_ctrl:1
	v_mov_b32_dpp v20, v18 row_ror:1 row_mask:0xf bank_mask:0xf bound_ctrl:1
	v_mov_b32_dpp v21, v19 row_ror:1 row_mask:0xf bank_mask:0xf bound_ctrl:1
	s_and_saveexec_b64 s[22:23], s[0:1]
	s_cbranch_execz .LBB0_661
	v_pk_add_f32 v[6:7], v[6:7], v[8:9]
	v_pk_add_f32 v[8:9], v[10:11], v[12:13]
	s_mov_b32 s10, 0x3d800000
	v_pk_mul_f32 v[8:9], v[8:9], s[10:11] op_sel_hi:[1,0]
	v_add_u32_e32 v10, 0x1ab00, v77
	ds_write_b128 v10, v[6:9]
	v_pk_add_f32 v[6:7], v[14:15], v[16:17]
	v_pk_add_f32 v[8:9], v[18:19], v[20:21]
	v_pk_mul_f32 v[6:7], v[6:7], s[10:11] op_sel_hi:[1,0]
	v_pk_mul_f32 v[8:9], v[8:9], s[10:11] op_sel_hi:[1,0]
	ds_write_b128 v10, v[6:9] offset:16
.LBB0_661:
	s_or_b64 exec, exec, s[22:23]
	v_lshlrev_b32_e32 v6, 2, v60
	s_add_i32 s7, 0, 0x1ae00
	v_add3_u32 v78, s7, v6, v24
	s_add_u32 s7, s20, s6
	s_addc_u32 s9, s21, 0
	s_add_u32 s20, s7, s8
	s_waitcnt vmcnt(3)
	v_cvt_f32_f16_sdwa v7, v22 dst_sel:DWORD dst_unused:UNUSED_PAD src0_sel:WORD_1
	v_cvt_f32_f16_e32 v6, v22
	s_addc_u32 s21, s9, 0
	v_lshl_add_u64 v[56:57], s[20:21], 0, v[2:3]
	s_mov_b64 s[20:21], 0x18000
	v_or_b32_e32 v54, 0x400, v55
	v_lshl_add_u64 v[16:17], v[28:29], 0, s[20:21]
	ds_write_b64 v78, v[6:7]
	ds_read_b128 v[198:201], v217 offset:36864
	ds_read_b128 v[202:205], v217 offset:36880
	ds_read2_b32 v[206:207], v221 offset1:16
	s_waitcnt lgkmcnt(0)
	v_mul_f32_e32 v210, 0x41800000, v200
	v_mul_f32_e32 v211, 0x41800000, v202
	v_mul_f32_e32 v212, 0x41800000, v204
	v_fma_f32 v213, -v204, v199, v203
	v_fma_f32 v121, -v198, v120, v121
	v_fma_f32 v124, -v210, v120, v124
	v_fma_f32 v125, -v211, v120, v125
	v_fma_f32 v123, -v198, v122, v123
	v_fma_f32 v126, -v210, v122, v126
	v_fma_f32 v127, -v211, v122, v127
	v_fma_f32 v129, -v198, v128, v129
	v_fma_f32 v132, -v210, v128, v132
	v_fma_f32 v133, -v211, v128, v133
	v_fma_f32 v131, -v198, v130, v131
	v_fma_f32 v134, -v210, v130, v134
	v_fma_f32 v135, -v211, v130, v135
	v_fma_f32 v182, -v199, v186, v182
	v_fma_f32 v183, -v199, v187, v183
	v_fma_f32 v184, -v199, v188, v184
	v_fma_f32 v185, -v199, v189, v185
	v_fma_f32 v125, -v212, v121, v125
	v_fma_f32 v127, -v212, v123, v127
	v_fma_f32 v133, -v212, v129, v133
	v_fma_f32 v135, -v212, v131, v135
	v_mul_f32_e32 v208, v206, v201
	v_mul_f32_e32 v209, v206, v213
	ds_write_b128 v219, v[120:123]
	v_fmac_f32_e32 v209, v207, v205
	ds_write_b128 v219, v[124:127] offset:256
	ds_write_b128 v219, v[128:131] offset:512
	ds_write_b128 v219, v[132:135] offset:768
	ds_write_b128 v219, v[182:185] offset:1280
	ds_write_b128 v223, v[206:209]
	v_or_b32_e32 v6, v16, v55
	v_mov_b32_e32 v7, v17
	v_or_b32_e32 v16, v16, v54
	v_lshlrev_b64 v[12:13], 1, v[6:7]
	v_lshlrev_b64 v[22:23], 1, v[16:17]
	v_lshl_add_u64 v[56:57], v[56:57], 0, v[32:33]
	s_mov_b32 s7, 0x30000
	v_lshl_add_u64 v[6:7], s[70:71], 0, v[12:13]
	v_lshl_add_u64 v[8:9], s[12:13], 0, v[12:13]
	v_lshl_add_u64 v[10:11], s[14:15], 0, v[12:13]
	v_lshl_add_u64 v[14:15], s[16:17], 0, v[12:13]
	v_lshl_add_u64 v[18:19], s[18:19], 0, v[12:13]
	v_lshl_add_u64 v[16:17], s[70:71], 0, v[22:23]
	v_lshl_add_u64 v[20:21], s[12:13], 0, v[22:23]
	v_lshl_add_u64 v[24:25], s[14:15], 0, v[22:23]
	v_add_co_u32_e32 v32, vcc, s7, v56
	global_load_dwordx2 v[6:7], v[6:7], off
	s_nop 0
	global_load_dwordx2 v[8:9], v[8:9], off
	s_nop 0
	global_load_dwordx2 v[10:11], v[10:11], off
	s_nop 0
	global_load_dwordx2 v[12:13], v[14:15], off
	s_nop 0
	global_load_dwordx2 v[14:15], v[18:19], off
	s_nop 0
	global_load_dwordx2 v[18:19], v[16:17], off
	s_nop 0
	global_load_dwordx2 v[16:17], v[20:21], off
	s_nop 0
	global_load_dwordx2 v[20:21], v[24:25], off
	v_lshl_add_u64 v[24:25], s[16:17], 0, v[22:23]
	v_lshl_add_u64 v[22:23], s[18:19], 0, v[22:23]
	v_addc_co_u32_e32 v33, vcc, 0, v57, vcc
	global_load_dwordx2 v[24:25], v[24:25], off
	s_nop 0
	global_load_dwordx2 v[22:23], v[22:23], off
	v_cvt_f32_f16_sdwa v67, v50 dst_sel:DWORD dst_unused:UNUSED_PAD src0_sel:WORD_1
	global_load_dword v79, v[32:33], off
	v_cvt_f32_f16_e32 v66, v50
	v_cvt_f32_f16_sdwa v33, v52 dst_sel:DWORD dst_unused:UNUSED_PAD src0_sel:WORD_1
	v_cvt_f32_f16_e32 v32, v52
	v_cvt_f32_f16_sdwa v71, v53 dst_sel:DWORD dst_unused:UNUSED_PAD src0_sel:WORD_1
	v_cvt_f32_f16_e32 v70, v53
	s_waitcnt vmcnt(12)
	v_cvt_f32_f16_sdwa v75, v44 dst_sel:DWORD dst_unused:UNUSED_PAD src0_sel:WORD_1
	v_cvt_f32_f16_e32 v74, v44
	v_cvt_f32_f16_sdwa v53, v51 dst_sel:DWORD dst_unused:UNUSED_PAD src0_sel:WORD_1
	v_cvt_f32_f16_e32 v52, v51
	v_cvt_f32_f16_sdwa v93, v45 dst_sel:DWORD dst_unused:UNUSED_PAD src0_sel:WORD_1
	v_cvt_f32_f16_e32 v92, v45
	v_cvt_f32_f16_sdwa v65, v42 dst_sel:DWORD dst_unused:UNUSED_PAD src0_sel:WORD_1
	v_cvt_f32_f16_e32 v64, v42
	v_pk_add_f32 v[68:69], v[66:67], 1.0 op_sel_hi:[1,0] neg_lo:[1,0] neg_hi:[1,0]
	v_cvt_f32_f16_sdwa v73, v48 dst_sel:DWORD dst_unused:UNUSED_PAD src0_sel:WORD_1
	v_cvt_f32_f16_e32 v72, v48
	v_cvt_f32_f16_sdwa v83, v46 dst_sel:DWORD dst_unused:UNUSED_PAD src0_sel:WORD_1
	v_cvt_f32_f16_e32 v82, v46
	v_cvt_f32_f16_sdwa v67, v43 dst_sel:DWORD dst_unused:UNUSED_PAD src0_sel:WORD_1
	v_cvt_f32_f16_e32 v66, v43
	v_cvt_f32_f16_sdwa v89, v49 dst_sel:DWORD dst_unused:UNUSED_PAD src0_sel:WORD_1
	v_cvt_f32_f16_e32 v88, v49
	v_cvt_f32_f16_sdwa v91, v47 dst_sel:DWORD dst_unused:UNUSED_PAD src0_sel:WORD_1
	v_cvt_f32_f16_e32 v90, v47
	v_pk_add_f32 v[32:33], v[32:33], 1.0 op_sel_hi:[1,0] neg_lo:[1,0] neg_hi:[1,0]
	v_pk_add_f32 v[86:87], v[70:71], 1.0 op_sel_hi:[1,0] neg_lo:[1,0] neg_hi:[1,0]
	v_pk_mul_f32 v[84:85], v[32:33], v[74:75]
	v_pk_add_f32 v[70:71], v[52:53], 1.0 op_sel_hi:[1,0] neg_lo:[1,0] neg_hi:[1,0]
	v_pk_mul_f32 v[94:95], v[86:87], v[92:93]
	v_pk_mul_f32 v[50:51], v[68:69], v[84:85]
	v_pk_mul_f32 v[52:53], v[70:71], v[94:95]
	v_add_u32_e32 v80, v59, v62
	s_waitcnt lgkmcnt(0)
	s_barrier
	v_pk_mul_f32 v[42:43], v[68:69], v[72:73]
	v_pk_mul_f32 v[44:45], v[70:71], v[88:89]
	v_pk_mul_f32 v[46:47], v[68:69], v[82:83]
	v_pk_mul_f32 v[48:49], v[70:71], v[90:91]
	v_pk_mul_f32 v[68:69], v[68:69], v[32:33]
	v_pk_mul_f32 v[70:71], v[70:71], v[86:87]
	v_mov_b32_e32 v120, v64
	v_mov_b32_e32 v121, v46
	v_mov_b32_e32 v122, v65
	v_mov_b32_e32 v123, v47
	v_mov_b32_e32 v124, v42
	v_mov_b32_e32 v125, v50
	v_mov_b32_e32 v126, v43
	v_mov_b32_e32 v127, v51
	v_mov_b32_e32 v128, v66
	v_mov_b32_e32 v129, v48
	v_mov_b32_e32 v130, v67
	v_mov_b32_e32 v131, v49
	v_mov_b32_e32 v132, v44
	v_mov_b32_e32 v133, v52
	v_mov_b32_e32 v134, v45
	v_mov_b32_e32 v135, v53
	ds_write_b128 v80, v[68:71] offset:1024
	v_cvt_f32_f16_e32 v51, v38
	v_cvt_f32_f16_sdwa v53, v38 dst_sel:DWORD dst_unused:UNUSED_PAD src0_sel:WORD_1
	v_cvt_f32_f16_e32 v50, v40
	v_cvt_f32_f16_sdwa v52, v40 dst_sel:DWORD dst_unused:UNUSED_PAD src0_sel:WORD_1
	v_cvt_f32_f16_e32 v63, v39
	v_cvt_f32_f16_sdwa v65, v39 dst_sel:DWORD dst_unused:UNUSED_PAD src0_sel:WORD_1
	v_cvt_f32_f16_e32 v62, v41
	v_cvt_f32_f16_sdwa v64, v41 dst_sel:DWORD dst_unused:UNUSED_PAD src0_sel:WORD_1
	v_mov_b32_e32 v42, v51
	v_mov_b32_e32 v43, v53
	v_mov_b32_e32 v44, v50
	v_mov_b32_e32 v45, v52
	v_mov_b32_e32 v38, v63
	v_mov_b32_e32 v39, v65
	v_pk_mul_f32 v[42:43], v[32:33], v[42:43]
	v_pk_mul_f32 v[46:47], v[32:33], v[44:45]
	v_mov_b32_e32 v32, v83
	v_pk_mul_f32 v[44:45], v[86:87], v[38:39]
	v_mov_b32_e32 v38, v62
	v_mov_b32_e32 v39, v64
	v_pk_fma_f32 v[40:41], v[82:83], v[50:51], 0 op_sel_hi:[0,1,0]
	v_pk_mul_f32 v[48:49], v[86:87], v[38:39]
	v_mov_b32_e32 v182, v42
	v_mov_b32_e32 v183, v43
	v_mov_b32_e32 v184, v44
	v_mov_b32_e32 v185, v45
	ds_write_b128 v80, v[46:49] offset:1536
	v_pk_fma_f32 v[32:33], v[32:33], v[52:53], v[40:41] op_sel_hi:[0,1,1]
	v_mov_b32_e32 v40, v73
	v_pk_fma_f32 v[44:45], v[72:73], v[50:51], 0 op_sel_hi:[0,1,0]
	v_pk_fma_f32 v[40:41], v[40:41], v[52:53], v[44:45] op_sel_hi:[0,1,1]
	v_pk_fma_f32 v[44:45], v[84:85], v[50:51], 0 op_sel_hi:[0,1,0]
	v_pk_fma_f32 v[44:45], v[84:85], v[52:53], v[44:45] op_sel:[1,0,0]
	v_mov_b32_e32 v38, v91
	v_pk_fma_f32 v[32:33], v[90:91], v[62:63], v[32:33] op_sel_hi:[0,1,1]
	v_mov_b32_e32 v42, v89
	v_pk_fma_f32 v[40:41], v[88:89], v[62:63], v[40:41] op_sel_hi:[0,1,1]
	v_pk_fma_f32 v[44:45], v[94:95], v[62:63], v[44:45] op_sel_hi:[0,1,1]
	v_pk_fma_f32 v[32:33], v[38:39], v[64:65], v[32:33] op_sel_hi:[0,1,1]
	v_pk_fma_f32 v[40:41], v[42:43], v[64:65], v[40:41] op_sel_hi:[0,1,1]
	v_pk_fma_f32 v[44:45], v[94:95], v[64:65], v[44:45] op_sel:[1,0,0]
	v_cvt_f32_f16_e32 v49, v34
	v_cvt_f32_f16_sdwa v51, v34 dst_sel:DWORD dst_unused:UNUSED_PAD src0_sel:WORD_1
	v_cvt_f32_f16_e32 v63, v35
	v_cvt_f32_f16_sdwa v65, v35 dst_sel:DWORD dst_unused:UNUSED_PAD src0_sel:WORD_1
	v_cvt_f32_f16_e32 v48, v36
	v_cvt_f32_f16_sdwa v50, v36 dst_sel:DWORD dst_unused:UNUSED_PAD src0_sel:WORD_1
	v_cvt_f32_f16_e32 v62, v37
	v_cvt_f32_f16_sdwa v64, v37 dst_sel:DWORD dst_unused:UNUSED_PAD src0_sel:WORD_1
	v_mov_b32_e32 v34, v49
	v_mov_b32_e32 v35, v51
	v_mov_b32_e32 v36, v63
	v_mov_b32_e32 v37, v65
	ds_write_b128 v80, v[34:37] offset:1792
	v_mov_b32_e32 v34, v48
	v_mov_b32_e32 v35, v50
	v_mov_b32_e32 v36, v62
	v_mov_b32_e32 v37, v64
	v_mov_b32_e32 v52, v75
	ds_write_b128 v80, v[34:37] offset:2048
	v_mov_b32_e32 v186, v34
	v_mov_b32_e32 v187, v35
	v_mov_b32_e32 v188, v36
	v_mov_b32_e32 v189, v37
	v_pk_fma_f32 v[34:35], v[74:75], v[48:49], 0 op_sel_hi:[0,1,0]
	v_pk_fma_f32 v[34:35], v[52:53], v[50:51], v[34:35] op_sel_hi:[0,1,1]
	v_mov_b32_e32 v66, v93
	v_pk_fma_f32 v[34:35], v[92:93], v[62:63], v[34:35] op_sel_hi:[0,1,1]
	v_pk_fma_f32 v[34:35], v[66:67], v[64:65], v[34:35] op_sel_hi:[0,1,1]
	v_mov_b32_dpp v38, v32 row_ror:8 row_mask:0xf bank_mask:0xf bound_ctrl:1
	v_mov_b32_dpp v39, v33 row_ror:8 row_mask:0xf bank_mask:0xf bound_ctrl:1
	v_mov_b32_dpp v42, v40 row_ror:8 row_mask:0xf bank_mask:0xf bound_ctrl:1
	v_mov_b32_dpp v43, v41 row_ror:8 row_mask:0xf bank_mask:0xf bound_ctrl:1
	v_mov_b32_dpp v46, v44 row_ror:8 row_mask:0xf bank_mask:0xf bound_ctrl:1
	v_mov_b32_dpp v47, v45 row_ror:8 row_mask:0xf bank_mask:0xf bound_ctrl:1
	v_mov_b32_dpp v36, v34 row_ror:8 row_mask:0xf bank_mask:0xf bound_ctrl:1
	v_mov_b32_dpp v37, v35 row_ror:8 row_mask:0xf bank_mask:0xf bound_ctrl:1
	v_pk_add_f32 v[32:33], v[32:33], v[38:39]
	v_pk_add_f32 v[40:41], v[40:41], v[42:43]
	v_pk_add_f32 v[44:45], v[44:45], v[46:47]
	v_pk_add_f32 v[34:35], v[34:35], v[36:37]
	v_mov_b32_dpp v38, v32 row_ror:4 row_mask:0xf bank_mask:0xf bound_ctrl:1
	v_mov_b32_dpp v39, v33 row_ror:4 row_mask:0xf bank_mask:0xf bound_ctrl:1
	v_mov_b32_dpp v42, v40 row_ror:4 row_mask:0xf bank_mask:0xf bound_ctrl:1
	v_mov_b32_dpp v43, v41 row_ror:4 row_mask:0xf bank_mask:0xf bound_ctrl:1
	v_mov_b32_dpp v46, v44 row_ror:4 row_mask:0xf bank_mask:0xf bound_ctrl:1
	v_mov_b32_dpp v47, v45 row_ror:4 row_mask:0xf bank_mask:0xf bound_ctrl:1
	v_mov_b32_dpp v36, v34 row_ror:4 row_mask:0xf bank_mask:0xf bound_ctrl:1
	v_mov_b32_dpp v37, v35 row_ror:4 row_mask:0xf bank_mask:0xf bound_ctrl:1
	v_pk_add_f32 v[32:33], v[32:33], v[38:39]
	v_pk_add_f32 v[40:41], v[40:41], v[42:43]
	v_pk_add_f32 v[44:45], v[44:45], v[46:47]
	v_pk_add_f32 v[34:35], v[34:35], v[36:37]
	v_mov_b32_dpp v38, v32 row_ror:2 row_mask:0xf bank_mask:0xf bound_ctrl:1
	v_mov_b32_dpp v39, v33 row_ror:2 row_mask:0xf bank_mask:0xf bound_ctrl:1
	v_mov_b32_dpp v42, v40 row_ror:2 row_mask:0xf bank_mask:0xf bound_ctrl:1
	v_mov_b32_dpp v43, v41 row_ror:2 row_mask:0xf bank_mask:0xf bound_ctrl:1
	v_mov_b32_dpp v46, v44 row_ror:2 row_mask:0xf bank_mask:0xf bound_ctrl:1
	v_mov_b32_dpp v47, v45 row_ror:2 row_mask:0xf bank_mask:0xf bound_ctrl:1
	v_mov_b32_dpp v36, v34 row_ror:2 row_mask:0xf bank_mask:0xf bound_ctrl:1
	v_mov_b32_dpp v37, v35 row_ror:2 row_mask:0xf bank_mask:0xf bound_ctrl:1
	v_pk_add_f32 v[32:33], v[32:33], v[38:39]
	v_pk_add_f32 v[40:41], v[40:41], v[42:43]
	v_pk_add_f32 v[44:45], v[44:45], v[46:47]
	v_pk_add_f32 v[34:35], v[34:35], v[36:37]
	v_mov_b32_dpp v38, v32 row_ror:1 row_mask:0xf bank_mask:0xf bound_ctrl:1
	v_mov_b32_dpp v39, v33 row_ror:1 row_mask:0xf bank_mask:0xf bound_ctrl:1
	v_mov_b32_dpp v42, v40 row_ror:1 row_mask:0xf bank_mask:0xf bound_ctrl:1
	v_mov_b32_dpp v43, v41 row_ror:1 row_mask:0xf bank_mask:0xf bound_ctrl:1
	v_mov_b32_dpp v46, v44 row_ror:1 row_mask:0xf bank_mask:0xf bound_ctrl:1
	v_mov_b32_dpp v47, v45 row_ror:1 row_mask:0xf bank_mask:0xf bound_ctrl:1
	v_mov_b32_dpp v36, v34 row_ror:1 row_mask:0xf bank_mask:0xf bound_ctrl:1
	v_mov_b32_dpp v37, v35 row_ror:1 row_mask:0xf bank_mask:0xf bound_ctrl:1
	s_and_saveexec_b64 s[20:21], s[0:1]
	s_cbranch_execz .LBB0_663
	v_pk_add_f32 v[38:39], v[32:33], v[38:39]
	v_pk_add_f32 v[32:33], v[40:41], v[42:43]
	s_mov_b32 s10, 0x3d800000
	v_pk_mul_f32 v[40:41], v[32:33], s[10:11] op_sel_hi:[1,0]
	v_pk_add_f32 v[32:33], v[44:45], v[46:47]
	v_pk_add_f32 v[34:35], v[34:35], v[36:37]
	v_pk_mul_f32 v[32:33], v[32:33], s[10:11] op_sel_hi:[1,0]
	v_pk_mul_f32 v[34:35], v[34:35], s[10:11] op_sel_hi:[1,0]
	ds_write_b128 v77, v[38:41] offset:36864
	ds_write_b128 v77, v[32:35] offset:36880
.LBB0_663:
	s_or_b64 exec, exec, s[20:21]
	s_add_u32 s20, s78, 0xf000000
	s_addc_u32 s21, s79, 0
	s_add_u32 s7, s20, s6
	s_addc_u32 s9, s21, 0
	s_add_u32 s22, s7, s8
	s_addc_u32 s23, s9, 0
	v_mov_b32_e32 v3, 0
	s_waitcnt vmcnt(11)
	v_cvt_f32_f16_sdwa v35, v61 dst_sel:DWORD dst_unused:UNUSED_PAD src0_sel:WORD_1
	v_cvt_f32_f16_e32 v34, v61
	v_lshl_add_u64 v[32:33], s[22:23], 0, v[2:3]
	s_mov_b64 s[22:23], 0x20000
	v_lshl_add_u64 v[38:39], v[28:29], 0, s[22:23]
	v_or_b32_e32 v28, v38, v55
	v_mov_b32_e32 v29, v39
	v_or_b32_e32 v38, v38, v54
	v_lshlrev_b64 v[30:31], 12, v[30:31]
	ds_write_b64 v1, v[34:35] offset:37632
	ds_read_b128 v[198:201], v216 offset:36864
	ds_read_b128 v[202:205], v216 offset:36880
	ds_read2_b32 v[206:207], v220 offset1:16
	s_waitcnt lgkmcnt(0)
	v_mul_f32_e32 v210, 0x41800000, v200
	v_mul_f32_e32 v211, 0x41800000, v202
	v_mul_f32_e32 v212, 0x41800000, v204
	v_fma_f32 v213, -v204, v199, v203
	v_fma_f32 v121, -v198, v120, v121
	v_fma_f32 v124, -v210, v120, v124
	v_fma_f32 v125, -v211, v120, v125
	v_fma_f32 v123, -v198, v122, v123
	v_fma_f32 v126, -v210, v122, v126
	v_fma_f32 v127, -v211, v122, v127
	v_fma_f32 v129, -v198, v128, v129
	v_fma_f32 v132, -v210, v128, v132
	v_fma_f32 v133, -v211, v128, v133
	v_fma_f32 v131, -v198, v130, v131
	v_fma_f32 v134, -v210, v130, v134
	v_fma_f32 v135, -v211, v130, v135
	v_fma_f32 v182, -v199, v186, v182
	v_fma_f32 v183, -v199, v187, v183
	v_fma_f32 v184, -v199, v188, v184
	v_fma_f32 v185, -v199, v189, v185
	v_fma_f32 v125, -v212, v121, v125
	v_fma_f32 v127, -v212, v123, v127
	v_fma_f32 v133, -v212, v129, v133
	v_fma_f32 v135, -v212, v131, v135
	v_mul_f32_e32 v208, v206, v201
	v_mul_f32_e32 v209, v206, v213
	ds_write_b128 v218, v[120:123]
	v_fmac_f32_e32 v209, v207, v205
	ds_write_b128 v218, v[124:127] offset:256
	ds_write_b128 v218, v[128:131] offset:512
	ds_write_b128 v218, v[132:135] offset:768
	ds_write_b128 v218, v[182:185] offset:1280
	ds_write_b128 v222, v[206:209]
	v_lshlrev_b64 v[34:35], 1, v[28:29]
	v_lshlrev_b64 v[44:45], 1, v[38:39]
	s_mov_b32 s7, 0x40000
	v_lshl_add_u64 v[52:53], v[32:33], 0, v[30:31]
	v_lshl_add_u64 v[28:29], s[70:71], 0, v[34:35]
	v_lshl_add_u64 v[30:31], s[12:13], 0, v[34:35]
	v_lshl_add_u64 v[32:33], s[14:15], 0, v[34:35]
	v_lshl_add_u64 v[36:37], s[16:17], 0, v[34:35]
	v_lshl_add_u64 v[40:41], s[18:19], 0, v[34:35]
	v_lshl_add_u64 v[38:39], s[70:71], 0, v[44:45]
	v_lshl_add_u64 v[42:43], s[12:13], 0, v[44:45]
	v_lshl_add_u64 v[46:47], s[14:15], 0, v[44:45]
	v_add_co_u32_e32 v48, vcc, s7, v56
	global_load_dwordx2 v[28:29], v[28:29], off
	s_nop 0
	global_load_dwordx2 v[30:31], v[30:31], off
	s_nop 0
	global_load_dwordx2 v[32:33], v[32:33], off
	s_nop 0
	global_load_dwordx2 v[34:35], v[36:37], off
	s_nop 0
	global_load_dwordx2 v[36:37], v[40:41], off
	s_nop 0
	global_load_dwordx2 v[40:41], v[38:39], off
	s_nop 0
	global_load_dwordx2 v[38:39], v[42:43], off
	s_nop 0
	global_load_dwordx2 v[42:43], v[46:47], off
	v_lshl_add_u64 v[46:47], s[16:17], 0, v[44:45]
	v_lshl_add_u64 v[44:45], s[18:19], 0, v[44:45]
	v_addc_co_u32_e32 v49, vcc, 0, v57, vcc
	global_load_dwordx2 v[46:47], v[46:47], off
	s_nop 0
	global_load_dwordx2 v[44:45], v[44:45], off
	v_or_b32_e32 v3, v60, v58
	global_load_dword v81, v[48:49], off
	v_lshlrev_b32_e32 v3, 6, v3
	v_add_u32_e32 v3, 0, v3
	v_bfe_u32 v177, v152, 4, 1
	v_sub_u32_e32 v176, 0, v177
	v_lshlrev_b32_e32 v178, 6, v177
	v_sub_u32_e32 v179, 64, v178
	v_bfe_u32 v177, v152, 1, 2
	v_add_u32_e32 v180, 0, v177
	v_and_b32_e32 v180, 3, v180
	v_lshlrev_b32_e32 v180, 4, v180
	v_add3_u32 v160, v3, v178, v180
	v_add3_u32 v164, v3, v179, v180
	v_add_u32_e32 v180, 1, v177
	v_and_b32_e32 v180, 3, v180
	v_lshlrev_b32_e32 v180, 4, v180
	v_add3_u32 v161, v3, v178, v180
	v_add3_u32 v165, v3, v179, v180
	v_add_u32_e32 v180, 2, v177
	v_and_b32_e32 v180, 3, v180
	v_lshlrev_b32_e32 v180, 4, v180
	v_add3_u32 v162, v3, v178, v180
	v_add3_u32 v166, v3, v179, v180
	v_add_u32_e32 v180, 3, v177
	v_and_b32_e32 v180, 3, v180
	v_lshlrev_b32_e32 v180, 4, v180
	v_add3_u32 v163, v3, v178, v180
	v_add3_u32 v167, v3, v179, v180
	v_add_u32_e32 v168, 0x11b00, v160
	v_add_u32_e32 v169, 0x11b00, v161
	v_add_u32_e32 v170, 0x11b00, v162
	v_add_u32_e32 v171, 0x11b00, v163
	v_add_u32_e32 v172, 0x11b00, v164
	v_add_u32_e32 v173, 0x11b00, v165
	v_add_u32_e32 v174, 0x11b00, v166
	v_add_u32_e32 v175, 0x11b00, v167
	ds_read_b128 v[120:123], v160 offset:39680
	ds_read_b128 v[124:127], v161 offset:39680
	ds_read_b128 v[128:131], v162 offset:39680
	ds_read_b128 v[132:135], v163 offset:39680
	ds_read_b128 v[136:139], v164 offset:39680
	ds_read_b128 v[140:143], v165 offset:39680
	ds_read_b128 v[144:147], v166 offset:39680
	ds_read_b128 v[148:151], v167 offset:39680
	s_movk_i32 s7, 0x7fff
	v_mov_b32_e32 v82, 1
	s_mov_b32 s9, 0xffff0000
	s_lshl_b32 s10, s2, 20
	s_and_b32 s10, s10, 0x4000000
	s_waitcnt lgkmcnt(0)
	v_pk_add_f32 v[120:121], v[120:121], v[124:125]
	v_pk_add_f32 v[122:123], v[122:123], v[126:127]
	v_pk_add_f32 v[128:129], v[128:129], v[132:133]
	v_pk_add_f32 v[130:131], v[130:131], v[134:135]
	v_pk_add_f32 v[120:121], v[120:121], v[128:129]
	v_pk_add_f32 v[122:123], v[122:123], v[130:131]
	v_pk_add_f32 v[120:121], v[120:121], v[122:123]
	v_add_f32_e32 v120, v120, v121
	v_pk_add_f32 v[136:137], v[136:137], v[140:141]
	v_pk_add_f32 v[138:139], v[138:139], v[142:143]
	v_pk_add_f32 v[144:145], v[144:145], v[148:149]
	v_pk_add_f32 v[146:147], v[146:147], v[150:151]
	v_pk_add_f32 v[136:137], v[136:137], v[144:145]
	v_pk_add_f32 v[138:139], v[138:139], v[146:147]
	v_pk_add_f32 v[136:137], v[136:137], v[138:139]
	v_add_f32_e32 v136, v136, v137
	v_bfi_b32 v49, v176, v136, v120
	v_bfi_b32 v48, v176, v120, v136
	v_and_b32_sdwa v50, v49, v82 dst_sel:DWORD dst_unused:UNUSED_PAD src0_sel:WORD_1 src1_sel:DWORD
	v_and_b32_sdwa v51, v48, v82 dst_sel:DWORD dst_unused:UNUSED_PAD src0_sel:WORD_1 src1_sel:DWORD
	v_add3_u32 v49, v49, v50, s7
	v_add3_u32 v48, v48, v51, s7
	v_lshrrev_b32_e32 v49, 16, v49
	v_and_or_b32 v48, v48, s9, v49
	global_store_dword v[52:53], v48, off
	v_lshlrev_b64 v[48:49], 12, v[4:5]
	v_lshl_add_u64 v[48:49], s[10:11], 0, v[48:49]
	s_lshl_b32 s10, s25, 5
	v_and_b32_e32 v50, 7, v153
	s_and_b32 s14, s10, 0x780
	v_lshlrev_b32_e32 v52, 2, v50
	v_lshlrev_b64 v[50:51], 11, v[4:5]
	v_or_b32_e32 v48, s14, v48
	s_and_b32 s15, s24, 0x60
	v_or_b32_e32 v50, s14, v50
	v_or3_b32 v48, v48, s15, v52
	v_or3_b32 v50, v50, s15, v52
	v_lshlrev_b64 v[52:53], 11, v[26:27]
	v_lshl_add_u64 v[48:49], s[78:79], 0, v[48:49]
	s_mov_b64 s[12:13], 0xf040000
	s_lshl_b32 s10, s2, 19
	v_lshl_or_b32 v52, v55, 1, v52
	v_lshl_add_u64 v[48:49], v[48:49], 0, s[12:13]
	s_and_b32 s10, s10, 0x2000000
	v_lshl_add_u64 v[50:51], s[70:71], 0, v[50:51]
	v_lshl_add_u64 v[26:27], s[70:71], 0, v[52:53]
	v_lshl_add_u64 v[52:53], s[78:79], 0, v[52:53]
	s_mov_b32 s12, 0x3d800000
	s_mov_b64 s[14:15], 0x40000
	s_mov_b32 s13, s11
	s_barrier
	s_branch .LBB0_665

.LBB0_665:
	s_waitcnt vmcnt(11)
	v_cvt_f32_f16_sdwa v59, v8 dst_sel:DWORD dst_unused:UNUSED_PAD src0_sel:WORD_1
	v_cvt_f32_f16_e32 v58, v8
	s_waitcnt vmcnt(10)
	v_cvt_f32_f16_sdwa v57, v16 dst_sel:DWORD dst_unused:UNUSED_PAD src0_sel:WORD_1
	v_cvt_f32_f16_e32 v56, v16
	v_cvt_f32_f16_sdwa v61, v9 dst_sel:DWORD dst_unused:UNUSED_PAD src0_sel:WORD_1
	v_pk_add_f32 v[70:71], v[58:59], 1.0 op_sel_hi:[1,0] neg_lo:[1,0] neg_hi:[1,0]
	v_cvt_f32_f16_sdwa v59, v17 dst_sel:DWORD dst_unused:UNUSED_PAD src0_sel:WORD_1
	v_cvt_f32_f16_e32 v58, v17
	v_cvt_f32_f16_e32 v60, v9
	s_waitcnt vmcnt(9)
	v_cvt_f32_f16_sdwa v87, v18 dst_sel:DWORD dst_unused:UNUSED_PAD src0_sel:WORD_1
	v_cvt_f32_f16_e32 v86, v18
	s_waitcnt vmcnt(3)
	v_cvt_f32_f16_sdwa v89, v24 dst_sel:DWORD dst_unused:UNUSED_PAD src0_sel:WORD_1
	v_cvt_f32_f16_e32 v88, v24
	v_cvt_f32_f16_sdwa v97, v25 dst_sel:DWORD dst_unused:UNUSED_PAD src0_sel:WORD_1
	v_cvt_f32_f16_e32 v96, v25
	v_cvt_f32_f16_sdwa v99, v19 dst_sel:DWORD dst_unused:UNUSED_PAD src0_sel:WORD_1
	v_cvt_f32_f16_e32 v98, v19
	v_cvt_f32_f16_sdwa v55, v12 dst_sel:DWORD dst_unused:UNUSED_PAD src0_sel:WORD_1
	v_cvt_f32_f16_e32 v54, v12
	v_pk_add_f32 v[74:75], v[56:57], 1.0 op_sel_hi:[1,0] neg_lo:[1,0] neg_hi:[1,0]
	v_cvt_f32_f16_sdwa v85, v6 dst_sel:DWORD dst_unused:UNUSED_PAD src0_sel:WORD_1
	v_cvt_f32_f16_e32 v84, v6
	v_cvt_f32_f16_sdwa v57, v13 dst_sel:DWORD dst_unused:UNUSED_PAD src0_sel:WORD_1
	v_cvt_f32_f16_e32 v56, v13
	v_cvt_f32_f16_sdwa v95, v7 dst_sel:DWORD dst_unused:UNUSED_PAD src0_sel:WORD_1
	v_cvt_f32_f16_e32 v94, v7
	v_pk_add_f32 v[92:93], v[58:59], 1.0 op_sel_hi:[1,0] neg_lo:[1,0] neg_hi:[1,0]
	v_pk_add_f32 v[72:73], v[60:61], 1.0 op_sel_hi:[1,0] neg_lo:[1,0] neg_hi:[1,0]
	v_pk_mul_f32 v[90:91], v[74:75], v[86:87]
	v_pk_mul_f32 v[62:63], v[70:71], v[88:89]
	v_pk_mul_f32 v[64:65], v[72:73], v[96:97]
	v_pk_mul_f32 v[100:101], v[92:93], v[98:99]
	v_pk_mul_f32 v[58:59], v[70:71], v[84:85]
	v_pk_mul_f32 v[60:61], v[72:73], v[94:95]
	v_pk_mul_f32 v[66:67], v[70:71], v[90:91]
	v_pk_mul_f32 v[68:69], v[72:73], v[100:101]
	v_pk_mul_f32 v[70:71], v[70:71], v[74:75]
	v_pk_mul_f32 v[72:73], v[72:73], v[92:93]
	v_mov_b32_e32 v120, v54
	v_mov_b32_e32 v121, v62
	v_mov_b32_e32 v122, v55
	v_mov_b32_e32 v123, v63
	v_mov_b32_e32 v124, v58
	v_mov_b32_e32 v125, v66
	v_mov_b32_e32 v126, v59
	v_mov_b32_e32 v127, v67
	v_mov_b32_e32 v128, v56
	v_mov_b32_e32 v129, v64
	v_mov_b32_e32 v130, v57
	v_mov_b32_e32 v131, v65
	v_mov_b32_e32 v132, v60
	v_mov_b32_e32 v133, v68
	v_mov_b32_e32 v134, v61
	v_mov_b32_e32 v135, v69
	ds_write_b128 v76, v[70:73] offset:1024
	v_cvt_f32_f16_e32 v62, v14
	v_cvt_f32_f16_sdwa v64, v14 dst_sel:DWORD dst_unused:UNUSED_PAD src0_sel:WORD_1
	v_cvt_f32_f16_e32 v63, v10
	v_cvt_f32_f16_sdwa v65, v10 dst_sel:DWORD dst_unused:UNUSED_PAD src0_sel:WORD_1
	v_cvt_f32_f16_e32 v69, v11
	v_cvt_f32_f16_sdwa v71, v11 dst_sel:DWORD dst_unused:UNUSED_PAD src0_sel:WORD_1
	v_cvt_f32_f16_e32 v68, v15
	v_cvt_f32_f16_sdwa v70, v15 dst_sel:DWORD dst_unused:UNUSED_PAD src0_sel:WORD_1
	v_mov_b32_e32 v56, v62
	v_mov_b32_e32 v57, v64
	v_mov_b32_e32 v54, v63
	v_mov_b32_e32 v55, v65
	v_pk_mul_f32 v[58:59], v[74:75], v[56:57]
	v_mov_b32_e32 v56, v69
	v_mov_b32_e32 v57, v71
	v_pk_mul_f32 v[54:55], v[74:75], v[54:55]
	v_pk_mul_f32 v[56:57], v[92:93], v[56:57]
	v_mov_b32_e32 v60, v68
	v_mov_b32_e32 v61, v70
	v_mov_b32_e32 v66, v89
	v_pk_mul_f32 v[60:61], v[92:93], v[60:61]
	v_mov_b32_e32 v182, v54
	v_mov_b32_e32 v183, v55
	v_mov_b32_e32 v184, v56
	v_mov_b32_e32 v185, v57
	ds_write_b128 v76, v[58:61] offset:1536
	v_pk_fma_f32 v[54:55], v[88:89], v[62:63], 0 op_sel_hi:[0,1,0]
	v_pk_fma_f32 v[54:55], v[66:67], v[64:65], v[54:55] op_sel_hi:[0,1,1]
	v_mov_b32_e32 v58, v85
	v_pk_fma_f32 v[66:67], v[84:85], v[62:63], 0 op_sel_hi:[0,1,0]
	v_pk_fma_f32 v[62:63], v[90:91], v[62:63], 0 op_sel_hi:[0,1,0]
	v_pk_fma_f32 v[58:59], v[58:59], v[64:65], v[66:67] op_sel_hi:[0,1,1]
	v_pk_fma_f32 v[62:63], v[90:91], v[64:65], v[62:63] op_sel:[1,0,0]
	v_mov_b32_e32 v72, v97
	v_pk_fma_f32 v[54:55], v[96:97], v[68:69], v[54:55] op_sel_hi:[0,1,1]
	v_mov_b32_e32 v60, v95
	v_pk_fma_f32 v[58:59], v[94:95], v[68:69], v[58:59] op_sel_hi:[0,1,1]
	v_pk_fma_f32 v[62:63], v[100:101], v[68:69], v[62:63] op_sel_hi:[0,1,1]
	v_pk_fma_f32 v[54:55], v[72:73], v[70:71], v[54:55] op_sel_hi:[0,1,1]
	v_pk_fma_f32 v[58:59], v[60:61], v[70:71], v[58:59] op_sel_hi:[0,1,1]
	v_pk_fma_f32 v[62:63], v[100:101], v[70:71], v[62:63] op_sel:[1,0,0]
	v_cvt_f32_f16_e32 v71, v20
	v_cvt_f32_f16_sdwa v73, v20 dst_sel:DWORD dst_unused:UNUSED_PAD src0_sel:WORD_1
	v_cvt_f32_f16_e32 v85, v21
	v_cvt_f32_f16_sdwa v89, v21 dst_sel:DWORD dst_unused:UNUSED_PAD src0_sel:WORD_1
	s_waitcnt vmcnt(13)
	v_cvt_f32_f16_e32 v70, v22
	v_cvt_f32_f16_sdwa v72, v22 dst_sel:DWORD dst_unused:UNUSED_PAD src0_sel:WORD_1
	v_cvt_f32_f16_e32 v84, v23
	v_cvt_f32_f16_sdwa v88, v23 dst_sel:DWORD dst_unused:UNUSED_PAD src0_sel:WORD_1
	v_mov_b32_e32 v66, v71
	v_mov_b32_e32 v67, v73
	v_mov_b32_e32 v68, v85
	v_mov_b32_e32 v69, v89
	ds_write_b128 v76, v[66:69] offset:1792
	v_mov_b32_e32 v66, v70
	v_mov_b32_e32 v67, v72
	v_mov_b32_e32 v68, v84
	v_mov_b32_e32 v69, v88
	v_mov_b32_e32 v74, v87
	ds_write_b128 v76, v[66:69] offset:2048
	v_mov_b32_e32 v186, v66
	v_mov_b32_e32 v187, v67
	v_mov_b32_e32 v188, v68
	v_mov_b32_e32 v189, v69
	v_pk_fma_f32 v[66:67], v[86:87], v[70:71], 0 op_sel_hi:[0,1,0]
	v_pk_fma_f32 v[66:67], v[74:75], v[72:73], v[66:67] op_sel_hi:[0,1,1]
	v_mov_b32_e32 v90, v99
	v_pk_fma_f32 v[66:67], v[98:99], v[84:85], v[66:67] op_sel_hi:[0,1,1]
	v_pk_fma_f32 v[66:67], v[90:91], v[88:89], v[66:67] op_sel_hi:[0,1,1]
	v_mov_b32_dpp v56, v54 row_ror:8 row_mask:0xf bank_mask:0xf bound_ctrl:1
	v_mov_b32_dpp v57, v55 row_ror:8 row_mask:0xf bank_mask:0xf bound_ctrl:1
	v_mov_b32_dpp v60, v58 row_ror:8 row_mask:0xf bank_mask:0xf bound_ctrl:1
	v_mov_b32_dpp v61, v59 row_ror:8 row_mask:0xf bank_mask:0xf bound_ctrl:1
	v_mov_b32_dpp v64, v62 row_ror:8 row_mask:0xf bank_mask:0xf bound_ctrl:1
	v_mov_b32_dpp v65, v63 row_ror:8 row_mask:0xf bank_mask:0xf bound_ctrl:1
	v_mov_b32_dpp v68, v66 row_ror:8 row_mask:0xf bank_mask:0xf bound_ctrl:1
	v_mov_b32_dpp v69, v67 row_ror:8 row_mask:0xf bank_mask:0xf bound_ctrl:1
	v_pk_add_f32 v[54:55], v[54:55], v[56:57]
	v_pk_add_f32 v[58:59], v[58:59], v[60:61]
	v_pk_add_f32 v[62:63], v[62:63], v[64:65]
	v_pk_add_f32 v[66:67], v[66:67], v[68:69]
	v_mov_b32_dpp v56, v54 row_ror:4 row_mask:0xf bank_mask:0xf bound_ctrl:1
	v_mov_b32_dpp v57, v55 row_ror:4 row_mask:0xf bank_mask:0xf bound_ctrl:1
	v_mov_b32_dpp v60, v58 row_ror:4 row_mask:0xf bank_mask:0xf bound_ctrl:1
	v_mov_b32_dpp v61, v59 row_ror:4 row_mask:0xf bank_mask:0xf bound_ctrl:1
	v_mov_b32_dpp v64, v62 row_ror:4 row_mask:0xf bank_mask:0xf bound_ctrl:1
	v_mov_b32_dpp v65, v63 row_ror:4 row_mask:0xf bank_mask:0xf bound_ctrl:1
	v_mov_b32_dpp v68, v66 row_ror:4 row_mask:0xf bank_mask:0xf bound_ctrl:1
	v_mov_b32_dpp v69, v67 row_ror:4 row_mask:0xf bank_mask:0xf bound_ctrl:1
	v_pk_add_f32 v[54:55], v[54:55], v[56:57]
	v_pk_add_f32 v[58:59], v[58:59], v[60:61]
	v_pk_add_f32 v[62:63], v[62:63], v[64:65]
	v_pk_add_f32 v[66:67], v[66:67], v[68:69]
	v_mov_b32_dpp v56, v54 row_ror:2 row_mask:0xf bank_mask:0xf bound_ctrl:1
	v_mov_b32_dpp v57, v55 row_ror:2 row_mask:0xf bank_mask:0xf bound_ctrl:1
	v_mov_b32_dpp v60, v58 row_ror:2 row_mask:0xf bank_mask:0xf bound_ctrl:1
	v_mov_b32_dpp v61, v59 row_ror:2 row_mask:0xf bank_mask:0xf bound_ctrl:1
	v_mov_b32_dpp v64, v62 row_ror:2 row_mask:0xf bank_mask:0xf bound_ctrl:1
	v_mov_b32_dpp v65, v63 row_ror:2 row_mask:0xf bank_mask:0xf bound_ctrl:1
	v_mov_b32_dpp v68, v66 row_ror:2 row_mask:0xf bank_mask:0xf bound_ctrl:1
	v_mov_b32_dpp v69, v67 row_ror:2 row_mask:0xf bank_mask:0xf bound_ctrl:1
	v_pk_add_f32 v[54:55], v[54:55], v[56:57]
	v_pk_add_f32 v[58:59], v[58:59], v[60:61]
	v_pk_add_f32 v[62:63], v[62:63], v[64:65]
	v_pk_add_f32 v[66:67], v[66:67], v[68:69]
	v_mov_b32_dpp v56, v54 row_ror:1 row_mask:0xf bank_mask:0xf bound_ctrl:1
	v_mov_b32_dpp v57, v55 row_ror:1 row_mask:0xf bank_mask:0xf bound_ctrl:1
	v_mov_b32_dpp v60, v58 row_ror:1 row_mask:0xf bank_mask:0xf bound_ctrl:1
	v_mov_b32_dpp v61, v59 row_ror:1 row_mask:0xf bank_mask:0xf bound_ctrl:1
	v_mov_b32_dpp v64, v62 row_ror:1 row_mask:0xf bank_mask:0xf bound_ctrl:1
	v_mov_b32_dpp v65, v63 row_ror:1 row_mask:0xf bank_mask:0xf bound_ctrl:1
	v_mov_b32_dpp v68, v66 row_ror:1 row_mask:0xf bank_mask:0xf bound_ctrl:1
	v_mov_b32_dpp v69, v67 row_ror:1 row_mask:0xf bank_mask:0xf bound_ctrl:1
	s_and_saveexec_b64 s[16:17], s[0:1]
	s_cbranch_execz .LBB0_667
	v_pk_add_f32 v[54:55], v[54:55], v[56:57]
	v_pk_add_f32 v[56:57], v[58:59], v[60:61]
	v_add_u32_e32 v58, 0x1ab00, v77
	v_pk_mul_f32 v[56:57], v[56:57], s[12:13] op_sel_hi:[1,0]
	ds_write_b128 v58, v[54:57]
	v_pk_add_f32 v[54:55], v[62:63], v[64:65]
	v_pk_add_f32 v[56:57], v[66:67], v[68:69]
	v_pk_mul_f32 v[54:55], v[54:55], s[12:13] op_sel_hi:[1,0]
	v_pk_mul_f32 v[56:57], v[56:57], s[12:13] op_sel_hi:[1,0]
	ds_write_b128 v58, v[54:57] offset:16
.LBB0_667:
	s_or_b64 exec, exec, s[16:17]
	s_waitcnt vmcnt(2)
	v_cvt_f32_f16_sdwa v55, v79 dst_sel:DWORD dst_unused:UNUSED_PAD src0_sel:WORD_1
	v_cvt_f32_f16_e32 v54, v79
	s_add_i32 s13, s13, 2
	s_cmpk_gt_u32 s13, 0x1fc
	v_lshl_add_u64 v[58:59], v[26:27], 0, s[10:11]
	ds_write_b64 v78, v[54:55]
	ds_read_b128 v[198:201], v217 offset:36864
	ds_read_b128 v[202:205], v217 offset:36880
	ds_read2_b32 v[206:207], v221 offset1:16
	s_waitcnt lgkmcnt(0)
	v_mul_f32_e32 v210, 0x41800000, v200
	v_mul_f32_e32 v211, 0x41800000, v202
	v_mul_f32_e32 v212, 0x41800000, v204
	v_fma_f32 v213, -v204, v199, v203
	v_fma_f32 v121, -v198, v120, v121
	v_fma_f32 v124, -v210, v120, v124
	v_fma_f32 v125, -v211, v120, v125
	v_fma_f32 v123, -v198, v122, v123
	v_fma_f32 v126, -v210, v122, v126
	v_fma_f32 v127, -v211, v122, v127
	v_fma_f32 v129, -v198, v128, v129
	v_fma_f32 v132, -v210, v128, v132
	v_fma_f32 v133, -v211, v128, v133
	v_fma_f32 v131, -v198, v130, v131
	v_fma_f32 v134, -v210, v130, v134
	v_fma_f32 v135, -v211, v130, v135
	v_fma_f32 v182, -v199, v186, v182
	v_fma_f32 v183, -v199, v187, v183
	v_fma_f32 v184, -v199, v188, v184
	v_fma_f32 v185, -v199, v189, v185
	v_fma_f32 v125, -v212, v121, v125
	v_fma_f32 v127, -v212, v123, v127
	v_fma_f32 v133, -v212, v129, v133
	v_fma_f32 v135, -v212, v131, v135
	v_mul_f32_e32 v208, v206, v201
	v_mul_f32_e32 v209, v206, v213
	ds_write_b128 v219, v[120:123]
	v_fmac_f32_e32 v209, v207, v205
	ds_write_b128 v219, v[124:127] offset:256
	ds_write_b128 v219, v[128:131] offset:512
	ds_write_b128 v219, v[132:135] offset:768
	ds_write_b128 v219, v[182:185] offset:1280
	ds_write_b128 v223, v[206:209]
	v_lshl_add_u64 v[56:57], v[52:53], 0, s[10:11]
	v_lshl_add_u64 v[54:55], v[50:51], 0, s[10:11]
	s_cbranch_scc1 .LBB0_669
	v_add_co_u32_e32 v10, vcc, 0x50000, v58
	s_nop 1
	v_addc_co_u32_e32 v11, vcc, 0, v59, vcc
	v_add_co_u32_e32 v12, vcc, 0x4050000, v58
	s_nop 1
	v_addc_co_u32_e32 v13, vcc, 0, v59, vcc
	v_add_co_u32_e32 v14, vcc, 0x8050000, v58
	s_nop 1
	v_addc_co_u32_e32 v15, vcc, 0, v59, vcc
	v_add_co_u32_e32 v24, vcc, 0x30050000, v56
	s_nop 1
	v_addc_co_u32_e32 v25, vcc, 0, v57, vcc
	v_add_co_u32_e32 v22, vcc, 0x34050000, v56
	s_nop 1
	v_addc_co_u32_e32 v23, vcc, 0, v57, vcc
	global_load_dwordx2 v[6:7], v[10:11], off
	global_load_dwordx2 v[8:9], v[12:13], off
	global_load_dwordx2 v[16:17], v[12:13], off offset:2048
	global_load_dwordx2 v[18:19], v[10:11], off offset:2048
	s_nop 0
	global_load_dwordx2 v[10:11], v[14:15], off
	global_load_dwordx2 v[20:21], v[14:15], off offset:2048
	global_load_dwordx2 v[12:13], v[24:25], off
	s_nop 0
	global_load_dwordx2 v[14:15], v[22:23], off
	s_nop 0
	global_load_dwordx2 v[22:23], v[22:23], off offset:2048
	s_nop 0
	global_load_dwordx2 v[24:25], v[24:25], off offset:2048
	v_add_co_u32_e32 v60, vcc, 0xc050000, v54
	s_nop 1
	v_addc_co_u32_e32 v61, vcc, 0, v55, vcc
	global_load_dword v79, v[60:61], off
.LBB0_669:
	ds_read_b128 v[120:123], v168 offset:39680
	ds_read_b128 v[124:127], v169 offset:39680
	ds_read_b128 v[128:131], v170 offset:39680
	ds_read_b128 v[132:135], v171 offset:39680
	ds_read_b128 v[136:139], v172 offset:39680
	ds_read_b128 v[140:143], v173 offset:39680
	ds_read_b128 v[144:147], v174 offset:39680
	ds_read_b128 v[148:151], v175 offset:39680
	s_cmpk_gt_u32 s13, 0x1fd
	s_cselect_b64 s[16:17], -1, 0
	s_nop 0
	s_nop 0
	s_nop 0
	s_waitcnt lgkmcnt(0)
	v_pk_add_f32 v[120:121], v[120:121], v[124:125]
	v_pk_add_f32 v[122:123], v[122:123], v[126:127]
	v_pk_add_f32 v[128:129], v[128:129], v[132:133]
	v_pk_add_f32 v[130:131], v[130:131], v[134:135]
	v_pk_add_f32 v[120:121], v[120:121], v[128:129]
	v_pk_add_f32 v[122:123], v[122:123], v[130:131]
	v_pk_add_f32 v[120:121], v[120:121], v[122:123]
	v_add_f32_e32 v120, v120, v121
	v_pk_add_f32 v[136:137], v[136:137], v[140:141]
	v_pk_add_f32 v[138:139], v[138:139], v[142:143]
	v_pk_add_f32 v[144:145], v[144:145], v[148:149]
	v_pk_add_f32 v[146:147], v[146:147], v[150:151]
	v_pk_add_f32 v[136:137], v[136:137], v[144:145]
	v_pk_add_f32 v[138:139], v[138:139], v[146:147]
	v_pk_add_f32 v[136:137], v[136:137], v[138:139]
	v_add_f32_e32 v136, v136, v137
	v_bfi_b32 v61, v176, v136, v120
	v_bfi_b32 v60, v176, v120, v136
	v_and_b32_sdwa v62, v61, v82 dst_sel:DWORD dst_unused:UNUSED_PAD src0_sel:WORD_1 src1_sel:DWORD
	v_and_b32_sdwa v63, v60, v82 dst_sel:DWORD dst_unused:UNUSED_PAD src0_sel:WORD_1 src1_sel:DWORD
	v_add3_u32 v61, v61, v62, s7
	v_add3_u32 v60, v60, v63, s7
	v_lshrrev_b32_e32 v61, 16, v61
	v_and_or_b32 v62, v60, s9, v61
	v_add_co_u32_e32 v60, vcc, 0xfffe0000, v48
	s_nop 1
	v_addc_co_u32_e32 v61, vcc, -1, v49, vcc
	s_and_b64 vcc, exec, s[16:17]
	global_store_dword v[60:61], v62, off
	s_barrier
	s_cbranch_vccnz .LBB0_673
	s_waitcnt vmcnt(11)
	v_cvt_f32_f16_sdwa v65, v30 dst_sel:DWORD dst_unused:UNUSED_PAD src0_sel:WORD_1
	v_cvt_f32_f16_e32 v64, v30
	s_waitcnt vmcnt(6)
	v_cvt_f32_f16_sdwa v63, v38 dst_sel:DWORD dst_unused:UNUSED_PAD src0_sel:WORD_1
	v_cvt_f32_f16_e32 v62, v38
	v_cvt_f32_f16_sdwa v67, v31 dst_sel:DWORD dst_unused:UNUSED_PAD src0_sel:WORD_1
	v_pk_add_f32 v[84:85], v[64:65], 1.0 op_sel_hi:[1,0] neg_lo:[1,0] neg_hi:[1,0]
	v_cvt_f32_f16_sdwa v65, v39 dst_sel:DWORD dst_unused:UNUSED_PAD src0_sel:WORD_1
	v_cvt_f32_f16_e32 v64, v39
	v_cvt_f32_f16_e32 v66, v31
	v_cvt_f32_f16_sdwa v93, v40 dst_sel:DWORD dst_unused:UNUSED_PAD src0_sel:WORD_1
	v_cvt_f32_f16_e32 v92, v40
	s_waitcnt vmcnt(4)
	v_cvt_f32_f16_sdwa v95, v46 dst_sel:DWORD dst_unused:UNUSED_PAD src0_sel:WORD_1
	v_cvt_f32_f16_e32 v94, v46
	v_cvt_f32_f16_sdwa v103, v47 dst_sel:DWORD dst_unused:UNUSED_PAD src0_sel:WORD_1
	v_cvt_f32_f16_e32 v102, v47
	v_cvt_f32_f16_sdwa v105, v41 dst_sel:DWORD dst_unused:UNUSED_PAD src0_sel:WORD_1
	v_cvt_f32_f16_e32 v104, v41
	v_cvt_f32_f16_sdwa v61, v34 dst_sel:DWORD dst_unused:UNUSED_PAD src0_sel:WORD_1
	v_cvt_f32_f16_e32 v60, v34
	v_pk_add_f32 v[88:89], v[62:63], 1.0 op_sel_hi:[1,0] neg_lo:[1,0] neg_hi:[1,0]
	v_cvt_f32_f16_sdwa v91, v28 dst_sel:DWORD dst_unused:UNUSED_PAD src0_sel:WORD_1
	v_cvt_f32_f16_e32 v90, v28
	v_cvt_f32_f16_sdwa v63, v35 dst_sel:DWORD dst_unused:UNUSED_PAD src0_sel:WORD_1
	v_cvt_f32_f16_e32 v62, v35
	v_cvt_f32_f16_sdwa v101, v29 dst_sel:DWORD dst_unused:UNUSED_PAD src0_sel:WORD_1
	v_cvt_f32_f16_e32 v100, v29
	v_pk_add_f32 v[98:99], v[64:65], 1.0 op_sel_hi:[1,0] neg_lo:[1,0] neg_hi:[1,0]
	v_pk_add_f32 v[86:87], v[66:67], 1.0 op_sel_hi:[1,0] neg_lo:[1,0] neg_hi:[1,0]
	v_pk_mul_f32 v[96:97], v[88:89], v[92:93]
	v_pk_mul_f32 v[68:69], v[84:85], v[94:95]
	v_pk_mul_f32 v[70:71], v[86:87], v[102:103]
	v_pk_mul_f32 v[106:107], v[98:99], v[104:105]
	v_pk_mul_f32 v[64:65], v[84:85], v[90:91]
	v_pk_mul_f32 v[66:67], v[86:87], v[100:101]
	v_pk_mul_f32 v[72:73], v[84:85], v[96:97]
	v_pk_mul_f32 v[74:75], v[86:87], v[106:107]
	v_pk_mul_f32 v[84:85], v[84:85], v[88:89]
	v_pk_mul_f32 v[86:87], v[86:87], v[98:99]
	v_mov_b32_e32 v120, v60
	v_mov_b32_e32 v121, v68
	v_mov_b32_e32 v122, v61
	v_mov_b32_e32 v123, v69
	v_mov_b32_e32 v124, v64
	v_mov_b32_e32 v125, v72
	v_mov_b32_e32 v126, v65
	v_mov_b32_e32 v127, v73
	v_mov_b32_e32 v128, v62
	v_mov_b32_e32 v129, v70
	v_mov_b32_e32 v130, v63
	v_mov_b32_e32 v131, v71
	v_mov_b32_e32 v132, v66
	v_mov_b32_e32 v133, v74
	v_mov_b32_e32 v134, v67
	v_mov_b32_e32 v135, v75
	ds_write_b128 v80, v[84:87] offset:1024
	v_cvt_f32_f16_e32 v68, v36
	v_cvt_f32_f16_sdwa v70, v36 dst_sel:DWORD dst_unused:UNUSED_PAD src0_sel:WORD_1
	v_cvt_f32_f16_e32 v69, v32
	v_cvt_f32_f16_sdwa v71, v32 dst_sel:DWORD dst_unused:UNUSED_PAD src0_sel:WORD_1
	v_cvt_f32_f16_e32 v75, v33
	v_cvt_f32_f16_sdwa v85, v33 dst_sel:DWORD dst_unused:UNUSED_PAD src0_sel:WORD_1
	v_cvt_f32_f16_e32 v74, v37
	v_cvt_f32_f16_sdwa v84, v37 dst_sel:DWORD dst_unused:UNUSED_PAD src0_sel:WORD_1
	v_mov_b32_e32 v62, v68
	v_mov_b32_e32 v63, v70
	v_mov_b32_e32 v60, v69
	v_mov_b32_e32 v61, v71
	v_pk_mul_f32 v[64:65], v[88:89], v[62:63]
	v_mov_b32_e32 v62, v75
	v_mov_b32_e32 v63, v85
	v_pk_mul_f32 v[60:61], v[88:89], v[60:61]
	v_pk_mul_f32 v[62:63], v[98:99], v[62:63]
	v_mov_b32_e32 v66, v74
	v_mov_b32_e32 v67, v84
	v_mov_b32_e32 v72, v95
	v_pk_mul_f32 v[66:67], v[98:99], v[66:67]
	v_mov_b32_e32 v182, v60
	v_mov_b32_e32 v183, v61
	v_mov_b32_e32 v184, v62
	v_mov_b32_e32 v185, v63
	ds_write_b128 v80, v[64:67] offset:1536
	v_pk_fma_f32 v[60:61], v[94:95], v[68:69], 0 op_sel_hi:[0,1,0]
	v_pk_fma_f32 v[60:61], v[72:73], v[70:71], v[60:61] op_sel_hi:[0,1,1]
	v_mov_b32_e32 v64, v91
	v_pk_fma_f32 v[72:73], v[90:91], v[68:69], 0 op_sel_hi:[0,1,0]
	v_pk_fma_f32 v[68:69], v[96:97], v[68:69], 0 op_sel_hi:[0,1,0]
	v_pk_fma_f32 v[64:65], v[64:65], v[70:71], v[72:73] op_sel_hi:[0,1,1]
	v_pk_fma_f32 v[68:69], v[96:97], v[70:71], v[68:69] op_sel:[1,0,0]
	v_mov_b32_e32 v86, v103
	v_pk_fma_f32 v[60:61], v[102:103], v[74:75], v[60:61] op_sel_hi:[0,1,1]
	v_mov_b32_e32 v66, v101
	v_pk_fma_f32 v[64:65], v[100:101], v[74:75], v[64:65] op_sel_hi:[0,1,1]
	v_pk_fma_f32 v[68:69], v[106:107], v[74:75], v[68:69] op_sel_hi:[0,1,1]
	v_pk_fma_f32 v[60:61], v[86:87], v[84:85], v[60:61] op_sel_hi:[0,1,1]
	v_pk_fma_f32 v[64:65], v[66:67], v[84:85], v[64:65] op_sel_hi:[0,1,1]
	v_pk_fma_f32 v[68:69], v[106:107], v[84:85], v[68:69] op_sel:[1,0,0]
	v_cvt_f32_f16_e32 v85, v42
	v_cvt_f32_f16_sdwa v87, v42 dst_sel:DWORD dst_unused:UNUSED_PAD src0_sel:WORD_1
	v_cvt_f32_f16_e32 v91, v43
	v_cvt_f32_f16_sdwa v95, v43 dst_sel:DWORD dst_unused:UNUSED_PAD src0_sel:WORD_1
	s_waitcnt vmcnt(3)
	v_cvt_f32_f16_e32 v84, v44
	v_cvt_f32_f16_sdwa v86, v44 dst_sel:DWORD dst_unused:UNUSED_PAD src0_sel:WORD_1
	v_cvt_f32_f16_e32 v90, v45
	v_cvt_f32_f16_sdwa v94, v45 dst_sel:DWORD dst_unused:UNUSED_PAD src0_sel:WORD_1
	v_mov_b32_e32 v72, v85
	v_mov_b32_e32 v73, v87
	v_mov_b32_e32 v74, v91
	v_mov_b32_e32 v75, v95
	ds_write_b128 v80, v[72:75] offset:1792
	v_mov_b32_e32 v72, v84
	v_mov_b32_e32 v73, v86
	v_mov_b32_e32 v74, v90
	v_mov_b32_e32 v75, v94
	v_mov_b32_e32 v88, v93
	ds_write_b128 v80, v[72:75] offset:2048
	v_mov_b32_e32 v186, v72
	v_mov_b32_e32 v187, v73
	v_mov_b32_e32 v188, v74
	v_mov_b32_e32 v189, v75
	v_pk_fma_f32 v[72:73], v[92:93], v[84:85], 0 op_sel_hi:[0,1,0]
	v_pk_fma_f32 v[72:73], v[88:89], v[86:87], v[72:73] op_sel_hi:[0,1,1]
	v_mov_b32_e32 v96, v105
	v_pk_fma_f32 v[72:73], v[104:105], v[90:91], v[72:73] op_sel_hi:[0,1,1]
	v_pk_fma_f32 v[72:73], v[96:97], v[94:95], v[72:73] op_sel_hi:[0,1,1]
	v_mov_b32_dpp v62, v60 row_ror:8 row_mask:0xf bank_mask:0xf bound_ctrl:1
	v_mov_b32_dpp v63, v61 row_ror:8 row_mask:0xf bank_mask:0xf bound_ctrl:1
	v_mov_b32_dpp v66, v64 row_ror:8 row_mask:0xf bank_mask:0xf bound_ctrl:1
	v_mov_b32_dpp v67, v65 row_ror:8 row_mask:0xf bank_mask:0xf bound_ctrl:1
	v_mov_b32_dpp v70, v68 row_ror:8 row_mask:0xf bank_mask:0xf bound_ctrl:1
	v_mov_b32_dpp v71, v69 row_ror:8 row_mask:0xf bank_mask:0xf bound_ctrl:1
	v_mov_b32_dpp v74, v72 row_ror:8 row_mask:0xf bank_mask:0xf bound_ctrl:1
	v_mov_b32_dpp v75, v73 row_ror:8 row_mask:0xf bank_mask:0xf bound_ctrl:1
	v_pk_add_f32 v[60:61], v[60:61], v[62:63]
	v_pk_add_f32 v[64:65], v[64:65], v[66:67]
	v_pk_add_f32 v[68:69], v[68:69], v[70:71]
	v_pk_add_f32 v[72:73], v[72:73], v[74:75]
	v_mov_b32_dpp v62, v60 row_ror:4 row_mask:0xf bank_mask:0xf bound_ctrl:1
	v_mov_b32_dpp v63, v61 row_ror:4 row_mask:0xf bank_mask:0xf bound_ctrl:1
	v_mov_b32_dpp v66, v64 row_ror:4 row_mask:0xf bank_mask:0xf bound_ctrl:1
	v_mov_b32_dpp v67, v65 row_ror:4 row_mask:0xf bank_mask:0xf bound_ctrl:1
	v_mov_b32_dpp v70, v68 row_ror:4 row_mask:0xf bank_mask:0xf bound_ctrl:1
	v_mov_b32_dpp v71, v69 row_ror:4 row_mask:0xf bank_mask:0xf bound_ctrl:1
	v_mov_b32_dpp v74, v72 row_ror:4 row_mask:0xf bank_mask:0xf bound_ctrl:1
	v_mov_b32_dpp v75, v73 row_ror:4 row_mask:0xf bank_mask:0xf bound_ctrl:1
	v_pk_add_f32 v[60:61], v[60:61], v[62:63]
	v_pk_add_f32 v[64:65], v[64:65], v[66:67]
	v_pk_add_f32 v[68:69], v[68:69], v[70:71]
	v_pk_add_f32 v[72:73], v[72:73], v[74:75]
	v_mov_b32_dpp v62, v60 row_ror:2 row_mask:0xf bank_mask:0xf bound_ctrl:1
	v_mov_b32_dpp v63, v61 row_ror:2 row_mask:0xf bank_mask:0xf bound_ctrl:1
	v_mov_b32_dpp v66, v64 row_ror:2 row_mask:0xf bank_mask:0xf bound_ctrl:1
	v_mov_b32_dpp v67, v65 row_ror:2 row_mask:0xf bank_mask:0xf bound_ctrl:1
	v_mov_b32_dpp v70, v68 row_ror:2 row_mask:0xf bank_mask:0xf bound_ctrl:1
	v_mov_b32_dpp v71, v69 row_ror:2 row_mask:0xf bank_mask:0xf bound_ctrl:1
	v_mov_b32_dpp v74, v72 row_ror:2 row_mask:0xf bank_mask:0xf bound_ctrl:1
	v_mov_b32_dpp v75, v73 row_ror:2 row_mask:0xf bank_mask:0xf bound_ctrl:1
	v_pk_add_f32 v[60:61], v[60:61], v[62:63]
	v_pk_add_f32 v[64:65], v[64:65], v[66:67]
	v_pk_add_f32 v[68:69], v[68:69], v[70:71]
	v_pk_add_f32 v[72:73], v[72:73], v[74:75]
	v_mov_b32_dpp v62, v60 row_ror:1 row_mask:0xf bank_mask:0xf bound_ctrl:1
	v_mov_b32_dpp v63, v61 row_ror:1 row_mask:0xf bank_mask:0xf bound_ctrl:1
	v_mov_b32_dpp v66, v64 row_ror:1 row_mask:0xf bank_mask:0xf bound_ctrl:1
	v_mov_b32_dpp v67, v65 row_ror:1 row_mask:0xf bank_mask:0xf bound_ctrl:1
	v_mov_b32_dpp v70, v68 row_ror:1 row_mask:0xf bank_mask:0xf bound_ctrl:1
	v_mov_b32_dpp v71, v69 row_ror:1 row_mask:0xf bank_mask:0xf bound_ctrl:1
	v_mov_b32_dpp v74, v72 row_ror:1 row_mask:0xf bank_mask:0xf bound_ctrl:1
	v_mov_b32_dpp v75, v73 row_ror:1 row_mask:0xf bank_mask:0xf bound_ctrl:1
	s_and_saveexec_b64 s[18:19], s[0:1]
	s_cbranch_execz .LBB0_672
	v_pk_add_f32 v[60:61], v[60:61], v[62:63]
	v_pk_add_f32 v[62:63], v[64:65], v[66:67]
	s_nop 0
	v_pk_mul_f32 v[62:63], v[62:63], s[12:13] op_sel_hi:[1,0]
	ds_write_b128 v77, v[60:63] offset:36864
	v_pk_add_f32 v[60:61], v[68:69], v[70:71]
	v_pk_add_f32 v[62:63], v[72:73], v[74:75]
	v_pk_mul_f32 v[60:61], v[60:61], s[12:13] op_sel_hi:[1,0]
	v_pk_mul_f32 v[62:63], v[62:63], s[12:13] op_sel_hi:[1,0]
	ds_write_b128 v77, v[60:63] offset:36880
.LBB0_672:
	s_or_b64 exec, exec, s[18:19]
	s_waitcnt vmcnt(2)
	v_cvt_f32_f16_sdwa v61, v81 dst_sel:DWORD dst_unused:UNUSED_PAD src0_sel:WORD_1
	v_cvt_f32_f16_e32 v60, v81
	ds_write_b64 v1, v[60:61] offset:37632
	ds_read_b128 v[198:201], v216 offset:36864
	ds_read_b128 v[202:205], v216 offset:36880
	ds_read2_b32 v[206:207], v220 offset1:16
	s_waitcnt lgkmcnt(0)
	v_mul_f32_e32 v210, 0x41800000, v200
	v_mul_f32_e32 v211, 0x41800000, v202
	v_mul_f32_e32 v212, 0x41800000, v204
	v_fma_f32 v213, -v204, v199, v203
	v_fma_f32 v121, -v198, v120, v121
	v_fma_f32 v124, -v210, v120, v124
	v_fma_f32 v125, -v211, v120, v125
	v_fma_f32 v123, -v198, v122, v123
	v_fma_f32 v126, -v210, v122, v126
	v_fma_f32 v127, -v211, v122, v127
	v_fma_f32 v129, -v198, v128, v129
	v_fma_f32 v132, -v210, v128, v132
	v_fma_f32 v133, -v211, v128, v133
	v_fma_f32 v131, -v198, v130, v131
	v_fma_f32 v134, -v210, v130, v134
	v_fma_f32 v135, -v211, v130, v135
	v_fma_f32 v182, -v199, v186, v182
	v_fma_f32 v183, -v199, v187, v183
	v_fma_f32 v184, -v199, v188, v184
	v_fma_f32 v185, -v199, v189, v185
	v_fma_f32 v125, -v212, v121, v125
	v_fma_f32 v127, -v212, v123, v127
	v_fma_f32 v133, -v212, v129, v133
	v_fma_f32 v135, -v212, v131, v135
	v_mul_f32_e32 v208, v206, v201
	v_mul_f32_e32 v209, v206, v213
	ds_write_b128 v218, v[120:123]
	v_fmac_f32_e32 v209, v207, v205
	ds_write_b128 v218, v[124:127] offset:256
	ds_write_b128 v218, v[128:131] offset:512
	ds_write_b128 v218, v[132:135] offset:768
	ds_write_b128 v218, v[182:185] offset:1280
	ds_write_b128 v222, v[206:209]
